# loop-edge edit: GEMM loop counter/pointer updates and exit compare moved from behind the last barrier into the head of the last MFMA segment (7 loops)
# baseline (speedup 1.0000x reference)
; #define PG8_STAGE(bufoff, gbase, voff) do { _Pragma("unroll") for (int _i = 0; _i < 2; ++_i) \
;         __builtin_amdgcn_global_load_lds((const unsigned*)((const char*)(gbase) + (voff)[_i]), (LAS unsigned*)(lds + (bufoff) + ldsw + _i * 8192), 16, 0, 0); } while (0)
; #define PG8_LDA(dst, b, h) do { _Pragma("unroll") for (int m = 0; m < 4; ++m) _Pragma("unroll") for (int k = 0; k < 2; ++k) dst[m][k] = *(const LAS bf16x8*)(lds + PG8_SA(b, h) + aoff + m * 2048 + k * 1024); } while (0)
; #define PG8_LDB(dst, b, h) do { _Pragma("unroll") for (int n = 0; n < 2; ++n) _Pragma("unroll") for (int k = 0; k < 2; ++k) dst[n][k] = *(const LAS bf16x8*)(lds + PG8_SB(b, h) + boff + n * 2048 + k * 1024); } while (0)
; #define PG8_MMA(ai, bj, At, Bt) do { __builtin_amdgcn_s_setprio(1); _Pragma("unroll") for (int m = 0; m < 4; ++m) _Pragma("unroll") for (int n = 0; n < 2; ++n) _Pragma("unroll") for (int k = 0; k < 2; ++k) \
;         acc[ai][bj][m][n] = __builtin_amdgcn_mfma_f32_16x16x32_bf16(Bt[n][k], At[m][k], acc[ai][bj][m][n], 0, 0, 0); __builtin_amdgcn_s_setprio(0); } while (0)
; #define PG8_WAIT_V(n) asm volatile("s_waitcnt vmcnt(" #n ")" ::: "memory")
; #define PG8_WAIT_L(n) asm volatile("s_waitcnt lgkmcnt(" #n ")" ::: "memory")
; #define PG8_BAR __builtin_amdgcn_s_barrier()
; #define PG8_SCHED __builtin_amdgcn_sched_barrier(0)
; template <class Epi, class Sched>
; __device__ __forceinline__ void gemm_phase(LAS unsigned char* lds, const int lda, const int ldb, const int K, const Sched& S, const Epi& E, int tid) {
;     ...
;         for (int t = 0; t < nt; t += 2) {
;             const bool last = (t == nt - 2);
;             const char* a1 = cA + (size_t)(t + 1) * kstep;
;             const char* a2 = last ? nA : cA + (size_t)(t + 2) * kstep; const char* b2 = last ? nB : cB + (size_t)(t + 2) * kstep;
;             const char* a3 = a2 + kstep; const char* b3 = b2 + kstep;
;             PG8_LDB(B0, 0, 0); PG8_LDB(B1, 0, 1); PG8_SCHED; PG8_LDA(At, 0, 0); PG8_STAGE(PG8_SA(1, 1), a1 + hA, voffA);
;             PG8_WAIT_V(8); PG8_WAIT_L(0); PG8_BAR; PG8_MMA(0, 0, At, B0); PG8_MMA(0, 1, At, B1); PG8_BAR; PG8_SCHED;
;             PG8_LDA(At, 0, 1); PG8_STAGE(PG8_SB(0, 0), b2, voffB); PG8_STAGE(PG8_SB(0, 1), b2 + hB, voffB); PG8_STAGE(PG8_SA(0, 0), a2, voffA);
;             PG8_WAIT_V(8); PG8_WAIT_L(0); PG8_BAR; PG8_MMA(1, 0, At, B0); PG8_MMA(1, 1, At, B1); PG8_BAR; PG8_SCHED;
.LBB0_91:
	s_add_u32 s10, s4, 0xfff80080
	s_addc_u32 s11, s5, -1
	s_add_i32 s22, 0, 0x10000
	s_cmp_eq_u32 s18, 28
	s_cselect_b32 s17, s3, s11
	s_cselect_b32 s16, s2, s10
	v_add_u32_e32 v0, s22, v174
	s_cselect_b32 s11, s15, s9
	s_cselect_b32 s10, s14, s7
	s_add_i32 s33, 0, 0x14000
	ds_read_b128 v[130:133], v0
	ds_read_b128 v[134:137], v0 offset:1024
	ds_read_b128 v[138:141], v0 offset:2048
	ds_read_b128 v[142:145], v0 offset:3072
	v_add_u32_e32 v0, s33, v174
	ds_read_b128 v[160:163], v0
	ds_read_b128 v[164:167], v0 offset:1024
	ds_read_b128 v[168:171], v0 offset:2048
	ds_read_b128 v[180:183], v0 offset:3072
	s_add_i32 m0, s21, 0xc000
	ds_read_b128 v[184:187], v178
	ds_read_b128 v[188:191], v178 offset:1024
	ds_read_b128 v[192:195], v178 offset:2048
	ds_read_b128 v[200:203], v178 offset:3072
	ds_read_b128 v[204:207], v178 offset:4096
	ds_read_b128 v[208:211], v178 offset:5120
	ds_read_b128 v[212:215], v178 offset:6144
	ds_read_b128 v[216:219], v178 offset:7168
	global_load_lds_dwordx4 v156, s[4:5]
	s_add_i32 m0, s21, 0xe000
	s_nop 0
	global_load_lds_dwordx4 v158, s[4:5]
	s_waitcnt vmcnt(8)
	s_waitcnt lgkmcnt(0)
	s_barrier
	s_setprio 1
	v_mfma_f32_16x16x32_bf16 v[126:129], v[130:133], v[184:187], v[126:129]
	v_mfma_f32_16x16x32_bf16 v[122:125], v[138:141], v[184:187], v[122:125]
	v_mfma_f32_16x16x32_bf16 v[118:121], v[130:133], v[192:195], v[118:121]
	v_mfma_f32_16x16x32_bf16 v[110:113], v[138:141], v[192:195], v[110:113]
	v_mfma_f32_16x16x32_bf16 v[102:105], v[130:133], v[204:207], v[102:105]
	v_mfma_f32_16x16x32_bf16 v[94:97], v[138:141], v[204:207], v[94:97]
	v_mfma_f32_16x16x32_bf16 v[86:89], v[130:133], v[212:215], v[86:89]
	v_mfma_f32_16x16x32_bf16 v[78:81], v[138:141], v[212:215], v[78:81]
	v_mfma_f32_16x16x32_bf16 v[126:129], v[134:137], v[188:191], v[126:129]
	v_mfma_f32_16x16x32_bf16 v[122:125], v[142:145], v[188:191], v[122:125]
	v_mfma_f32_16x16x32_bf16 v[118:121], v[134:137], v[200:203], v[118:121]
	v_mfma_f32_16x16x32_bf16 v[110:113], v[142:145], v[200:203], v[110:113]
	v_mfma_f32_16x16x32_bf16 v[102:105], v[134:137], v[208:211], v[102:105]
	v_mfma_f32_16x16x32_bf16 v[94:97], v[142:145], v[208:211], v[94:97]
	v_mfma_f32_16x16x32_bf16 v[86:89], v[134:137], v[216:219], v[86:89]
	v_mfma_f32_16x16x32_bf16 v[78:81], v[142:145], v[216:219], v[78:81]
	s_setprio 0
	s_setprio 1
	v_mfma_f32_16x16x32_bf16 v[114:117], v[160:163], v[184:187], v[114:117]
	v_mfma_f32_16x16x32_bf16 v[106:109], v[168:171], v[184:187], v[106:109]
	v_mfma_f32_16x16x32_bf16 v[98:101], v[160:163], v[192:195], v[98:101]
	v_mfma_f32_16x16x32_bf16 v[90:93], v[168:171], v[192:195], v[90:93]
	v_mfma_f32_16x16x32_bf16 v[82:85], v[160:163], v[204:207], v[82:85]
	v_mfma_f32_16x16x32_bf16 v[74:77], v[168:171], v[204:207], v[74:77]
	v_mfma_f32_16x16x32_bf16 v[70:73], v[160:163], v[212:215], v[70:73]
	v_mfma_f32_16x16x32_bf16 v[66:69], v[168:171], v[212:215], v[66:69]
	v_mfma_f32_16x16x32_bf16 v[114:117], v[164:167], v[188:191], v[114:117]
	v_mfma_f32_16x16x32_bf16 v[106:109], v[180:183], v[188:191], v[106:109]
	v_mfma_f32_16x16x32_bf16 v[98:101], v[164:167], v[200:203], v[98:101]
	v_mfma_f32_16x16x32_bf16 v[90:93], v[180:183], v[200:203], v[90:93]
	v_mfma_f32_16x16x32_bf16 v[82:85], v[164:167], v[208:211], v[82:85]
	v_mfma_f32_16x16x32_bf16 v[74:77], v[180:183], v[208:211], v[74:77]
	v_mfma_f32_16x16x32_bf16 v[70:73], v[164:167], v[216:219], v[70:73]
	v_mfma_f32_16x16x32_bf16 v[66:69], v[180:183], v[216:219], v[66:69]
	s_setprio 0
	s_barrier
	s_add_u32 s98, s10, s30
	s_addc_u32 s99, s11, s31
	s_add_u32 s100, s16, s30
	s_addc_u32 s101, s17, s31
	s_add_i32 s22, s22, s20
	s_mov_b32 m0, s22
	ds_read_b128 v[184:187], v178 offset:16384
	ds_read_b128 v[188:191], v178 offset:17408
	ds_read_b128 v[192:195], v178 offset:18432
	ds_read_b128 v[200:203], v178 offset:19456
	ds_read_b128 v[204:207], v178 offset:20480
	ds_read_b128 v[208:211], v178 offset:21504
	ds_read_b128 v[212:215], v178 offset:22528
	ds_read_b128 v[216:219], v178 offset:23552
	global_load_lds_dwordx4 v148, s[10:11]
	s_add_i32 m0, s22, 0x2000
	s_add_u32 s22, s10, 0x80000
	s_addc_u32 s23, s11, 0
	s_add_i32 s33, s33, s20
	global_load_lds_dwordx4 v152, s[10:11]
	s_mov_b32 m0, s33
	s_nop 0
	global_load_lds_dwordx4 v148, s[22:23]
	s_add_i32 m0, s33, 0x2000
	s_nop 0
	global_load_lds_dwordx4 v152, s[22:23]
	s_mov_b32 m0, s21
	s_nop 0
	global_load_lds_dwordx4 v146, s[16:17]
	s_mov_b32 m0, s25
	s_nop 0
	global_load_lds_dwordx4 v150, s[16:17]
	s_waitcnt vmcnt(8)
	s_waitcnt lgkmcnt(0)
	s_barrier
	s_setprio 1
	v_mfma_f32_16x16x32_bf16 v[62:65], v[130:133], v[184:187], v[62:65]
	v_mfma_f32_16x16x32_bf16 v[58:61], v[138:141], v[184:187], v[58:61]
	v_mfma_f32_16x16x32_bf16 v[54:57], v[130:133], v[192:195], v[54:57]
	v_mfma_f32_16x16x32_bf16 v[46:49], v[138:141], v[192:195], v[46:49]
	v_mfma_f32_16x16x32_bf16 v[38:41], v[130:133], v[204:207], v[38:41]
	v_mfma_f32_16x16x32_bf16 v[30:33], v[138:141], v[204:207], v[30:33]
	v_mfma_f32_16x16x32_bf16 v[22:25], v[130:133], v[212:215], v[22:25]
	v_mfma_f32_16x16x32_bf16 v[14:17], v[138:141], v[212:215], v[14:17]
	v_mfma_f32_16x16x32_bf16 v[62:65], v[134:137], v[188:191], v[62:65]
	v_mfma_f32_16x16x32_bf16 v[58:61], v[142:145], v[188:191], v[58:61]
	v_mfma_f32_16x16x32_bf16 v[54:57], v[134:137], v[200:203], v[54:57]
	v_mfma_f32_16x16x32_bf16 v[46:49], v[142:145], v[200:203], v[46:49]
	v_mfma_f32_16x16x32_bf16 v[38:41], v[134:137], v[208:211], v[38:41]
	v_mfma_f32_16x16x32_bf16 v[30:33], v[142:145], v[208:211], v[30:33]
	v_mfma_f32_16x16x32_bf16 v[22:25], v[134:137], v[216:219], v[22:25]
	v_mfma_f32_16x16x32_bf16 v[14:17], v[142:145], v[216:219], v[14:17]
	s_setprio 0
	s_setprio 1
	v_mfma_f32_16x16x32_bf16 v[50:53], v[160:163], v[184:187], v[50:53]
	v_mfma_f32_16x16x32_bf16 v[42:45], v[168:171], v[184:187], v[42:45]
	v_mfma_f32_16x16x32_bf16 v[34:37], v[160:163], v[192:195], v[34:37]
	v_mfma_f32_16x16x32_bf16 v[26:29], v[168:171], v[192:195], v[26:29]
	v_mfma_f32_16x16x32_bf16 v[18:21], v[160:163], v[204:207], v[18:21]
	v_mfma_f32_16x16x32_bf16 v[10:13], v[168:171], v[204:207], v[10:13]
	v_mfma_f32_16x16x32_bf16 v[6:9], v[160:163], v[212:215], v[6:9]
	v_mfma_f32_16x16x32_bf16 v[2:5], v[168:171], v[212:215], v[2:5]
	v_mfma_f32_16x16x32_bf16 v[50:53], v[164:167], v[188:191], v[50:53]
	v_mfma_f32_16x16x32_bf16 v[42:45], v[180:183], v[188:191], v[42:45]
	v_mfma_f32_16x16x32_bf16 v[34:37], v[164:167], v[200:203], v[34:37]
	v_mfma_f32_16x16x32_bf16 v[26:29], v[180:183], v[200:203], v[26:29]
	v_mfma_f32_16x16x32_bf16 v[18:21], v[164:167], v[208:211], v[18:21]
	v_mfma_f32_16x16x32_bf16 v[10:13], v[180:183], v[208:211], v[10:13]
	v_mfma_f32_16x16x32_bf16 v[6:9], v[164:167], v[216:219], v[6:9]
	v_mfma_f32_16x16x32_bf16 v[2:5], v[180:183], v[216:219], v[2:5]
	s_setprio 0
	s_barrier
; #define PG8_STAGE(bufoff, gbase, voff) do { _Pragma("unroll") for (int _i = 0; _i < 2; ++_i) \
;         __builtin_amdgcn_global_load_lds((const unsigned*)((const char*)(gbase) + (voff)[_i]), (LAS unsigned*)(lds + (bufoff) + ldsw + _i * 8192), 16, 0, 0); } while (0)
; #define PG8_LDA(dst, b, h) do { _Pragma("unroll") for (int m = 0; m < 4; ++m) _Pragma("unroll") for (int k = 0; k < 2; ++k) dst[m][k] = *(const LAS bf16x8*)(lds + PG8_SA(b, h) + aoff + m * 2048 + k * 1024); } while (0)
; #define PG8_LDB(dst, b, h) do { _Pragma("unroll") for (int n = 0; n < 2; ++n) _Pragma("unroll") for (int k = 0; k < 2; ++k) dst[n][k] = *(const LAS bf16x8*)(lds + PG8_SB(b, h) + boff + n * 2048 + k * 1024); } while (0)
; #define PG8_MMA(ai, bj, At, Bt) do { __builtin_amdgcn_s_setprio(1); _Pragma("unroll") for (int m = 0; m < 4; ++m) _Pragma("unroll") for (int n = 0; n < 2; ++n) _Pragma("unroll") for (int k = 0; k < 2; ++k) \
;         acc[ai][bj][m][n] = __builtin_amdgcn_mfma_f32_16x16x32_bf16(Bt[n][k], At[m][k], acc[ai][bj][m][n], 0, 0, 0); __builtin_amdgcn_s_setprio(0); } while (0)
; #define PG8_WAIT_V(n) asm volatile("s_waitcnt vmcnt(" #n ")" ::: "memory")
; #define PG8_WAIT_L(n) asm volatile("s_waitcnt lgkmcnt(" #n ")" ::: "memory")
; #define PG8_BAR __builtin_amdgcn_s_barrier()
; #define PG8_SCHED __builtin_amdgcn_sched_barrier(0)
; template <class Epi, class Sched>
; __device__ __forceinline__ void gemm_phase(LAS unsigned char* lds, const int lda, const int ldb, const int K, const Sched& S, const Epi& E, int tid) {
;     ...
;             PG8_LDB(B0, 1, 0); PG8_LDB(B1, 1, 1); PG8_SCHED; PG8_LDA(At, 1, 0); PG8_STAGE(PG8_SA(0, 1), a2 + hA, voffA);
;             PG8_WAIT_V(8); PG8_WAIT_L(0); PG8_BAR; PG8_MMA(0, 0, At, B0); PG8_MMA(0, 1, At, B1); PG8_BAR; PG8_SCHED;
;             PG8_LDA(At, 1, 1); PG8_STAGE(PG8_SB(1, 0), b3, voffB); PG8_STAGE(PG8_SB(1, 1), b3 + hB, voffB); PG8_STAGE(PG8_SA(1, 0), a3, voffA);
;             PG8_WAIT_V(8); PG8_WAIT_L(0); PG8_BAR; PG8_MMA(1, 0, At, B0); PG8_MMA(1, 1, At, B1); PG8_BAR; PG8_SCHED;
;         }
;         if (wr == 0) PG8_BAR;
	s_add_i32 s22, 0, 0x18000
	v_add_u32_e32 v0, s22, v174
	s_add_i32 s23, 0, 0x1c000
	ds_read_b128 v[130:133], v0
	ds_read_b128 v[134:137], v0 offset:1024
	ds_read_b128 v[138:141], v0 offset:2048
	ds_read_b128 v[142:145], v0 offset:3072
	v_add_u32_e32 v0, s23, v174
	ds_read_b128 v[160:163], v0
	ds_read_b128 v[164:167], v0 offset:1024
	ds_read_b128 v[168:171], v0 offset:2048
	ds_read_b128 v[180:183], v0 offset:3072
	s_add_u32 s16, s16, 0x80000
	s_addc_u32 s17, s17, 0
	s_mov_b32 m0, s26
	ds_read_b128 v[184:187], v178 offset:32768
	ds_read_b128 v[188:191], v178 offset:33792
	ds_read_b128 v[192:195], v178 offset:34816
	ds_read_b128 v[200:203], v178 offset:35840
	ds_read_b128 v[204:207], v178 offset:36864
	ds_read_b128 v[208:211], v178 offset:37888
	ds_read_b128 v[212:215], v178 offset:38912
	ds_read_b128 v[216:219], v178 offset:39936
	global_load_lds_dwordx4 v146, s[16:17]
	s_mov_b32 m0, s27
	s_nop 0
	global_load_lds_dwordx4 v150, s[16:17]
	s_waitcnt vmcnt(8)
	s_waitcnt lgkmcnt(0)
	s_barrier
	s_setprio 1
	v_mfma_f32_16x16x32_bf16 v[126:129], v[130:133], v[184:187], v[126:129]
	v_mfma_f32_16x16x32_bf16 v[122:125], v[138:141], v[184:187], v[122:125]
	v_mfma_f32_16x16x32_bf16 v[118:121], v[130:133], v[192:195], v[118:121]
	v_mfma_f32_16x16x32_bf16 v[110:113], v[138:141], v[192:195], v[110:113]
	v_mfma_f32_16x16x32_bf16 v[102:105], v[130:133], v[204:207], v[102:105]
	v_mfma_f32_16x16x32_bf16 v[94:97], v[138:141], v[204:207], v[94:97]
	v_mfma_f32_16x16x32_bf16 v[86:89], v[130:133], v[212:215], v[86:89]
	v_mfma_f32_16x16x32_bf16 v[78:81], v[138:141], v[212:215], v[78:81]
	v_mfma_f32_16x16x32_bf16 v[126:129], v[134:137], v[188:191], v[126:129]
	v_mfma_f32_16x16x32_bf16 v[122:125], v[142:145], v[188:191], v[122:125]
	v_mfma_f32_16x16x32_bf16 v[118:121], v[134:137], v[200:203], v[118:121]
	v_mfma_f32_16x16x32_bf16 v[110:113], v[142:145], v[200:203], v[110:113]
	v_mfma_f32_16x16x32_bf16 v[102:105], v[134:137], v[208:211], v[102:105]
	v_mfma_f32_16x16x32_bf16 v[94:97], v[142:145], v[208:211], v[94:97]
	v_mfma_f32_16x16x32_bf16 v[86:89], v[134:137], v[216:219], v[86:89]
	v_mfma_f32_16x16x32_bf16 v[78:81], v[142:145], v[216:219], v[78:81]
	s_setprio 0
	s_setprio 1
	v_mfma_f32_16x16x32_bf16 v[114:117], v[160:163], v[184:187], v[114:117]
	v_mfma_f32_16x16x32_bf16 v[106:109], v[168:171], v[184:187], v[106:109]
	v_mfma_f32_16x16x32_bf16 v[98:101], v[160:163], v[192:195], v[98:101]
	v_mfma_f32_16x16x32_bf16 v[90:93], v[168:171], v[192:195], v[90:93]
	v_mfma_f32_16x16x32_bf16 v[82:85], v[160:163], v[204:207], v[82:85]
	v_mfma_f32_16x16x32_bf16 v[74:77], v[168:171], v[204:207], v[74:77]
	v_mfma_f32_16x16x32_bf16 v[70:73], v[160:163], v[212:215], v[70:73]
	v_mfma_f32_16x16x32_bf16 v[66:69], v[168:171], v[212:215], v[66:69]
	v_mfma_f32_16x16x32_bf16 v[114:117], v[164:167], v[188:191], v[114:117]
	v_mfma_f32_16x16x32_bf16 v[106:109], v[180:183], v[188:191], v[106:109]
	v_mfma_f32_16x16x32_bf16 v[98:101], v[164:167], v[200:203], v[98:101]
	v_mfma_f32_16x16x32_bf16 v[90:93], v[180:183], v[200:203], v[90:93]
	v_mfma_f32_16x16x32_bf16 v[82:85], v[164:167], v[208:211], v[82:85]
	v_mfma_f32_16x16x32_bf16 v[74:77], v[180:183], v[208:211], v[74:77]
	v_mfma_f32_16x16x32_bf16 v[70:73], v[164:167], v[216:219], v[70:73]
	v_mfma_f32_16x16x32_bf16 v[66:69], v[180:183], v[216:219], v[66:69]
	s_setprio 0
	s_barrier
	s_add_i32 s16, s22, s20
	s_mov_b32 m0, s16
	ds_read_b128 v[184:187], v178 offset:49152
	ds_read_b128 v[188:191], v178 offset:50176
	ds_read_b128 v[192:195], v178 offset:51200
	ds_read_b128 v[200:203], v178 offset:52224
	ds_read_b128 v[204:207], v178 offset:53248
	ds_read_b128 v[208:211], v178 offset:54272
	ds_read_b128 v[212:215], v178 offset:55296
	ds_read_b128 v[216:219], v178 offset:56320
	global_load_lds_dwordx4 v148, s[98:99]
	s_add_i32 m0, s16, 0x2000
	s_add_u32 s10, s10, 0x80080
	s_addc_u32 s11, s11, 0
	s_add_i32 s16, s23, s20
	global_load_lds_dwordx4 v152, s[98:99]
	s_mov_b32 m0, s16
	s_nop 0
	global_load_lds_dwordx4 v148, s[10:11]
	s_add_i32 m0, s16, 0x2000
	s_nop 0
	global_load_lds_dwordx4 v152, s[10:11]
	s_mov_b32 m0, s54
	s_nop 0
	global_load_lds_dwordx4 v146, s[100:101]
	s_mov_b32 m0, s55
	s_nop 0
	global_load_lds_dwordx4 v150, s[100:101]
	s_waitcnt vmcnt(8)
	s_waitcnt lgkmcnt(0)
	s_barrier
	s_setprio 1
	s_add_i32 s18, s18, 2
	s_add_u32 s4, s4, 0x100
	s_addc_u32 s5, s5, 0
	s_add_u32 s7, s7, 0x100
	s_addc_u32 s9, s9, 0
	s_cmp_gt_u32 s18, 29
	v_mfma_f32_16x16x32_bf16 v[62:65], v[130:133], v[184:187], v[62:65]
	v_mfma_f32_16x16x32_bf16 v[58:61], v[138:141], v[184:187], v[58:61]
	v_mfma_f32_16x16x32_bf16 v[54:57], v[130:133], v[192:195], v[54:57]
	v_mfma_f32_16x16x32_bf16 v[46:49], v[138:141], v[192:195], v[46:49]
	v_mfma_f32_16x16x32_bf16 v[38:41], v[130:133], v[204:207], v[38:41]
	v_mfma_f32_16x16x32_bf16 v[30:33], v[138:141], v[204:207], v[30:33]
	v_mfma_f32_16x16x32_bf16 v[22:25], v[130:133], v[212:215], v[22:25]
	v_mfma_f32_16x16x32_bf16 v[14:17], v[138:141], v[212:215], v[14:17]
	v_mfma_f32_16x16x32_bf16 v[62:65], v[134:137], v[188:191], v[62:65]
	v_mfma_f32_16x16x32_bf16 v[58:61], v[142:145], v[188:191], v[58:61]
	v_mfma_f32_16x16x32_bf16 v[54:57], v[134:137], v[200:203], v[54:57]
	v_mfma_f32_16x16x32_bf16 v[46:49], v[142:145], v[200:203], v[46:49]
	v_mfma_f32_16x16x32_bf16 v[38:41], v[134:137], v[208:211], v[38:41]
	v_mfma_f32_16x16x32_bf16 v[30:33], v[142:145], v[208:211], v[30:33]
	v_mfma_f32_16x16x32_bf16 v[22:25], v[134:137], v[216:219], v[22:25]
	v_mfma_f32_16x16x32_bf16 v[14:17], v[142:145], v[216:219], v[14:17]
	s_setprio 0
	s_setprio 1
	v_mfma_f32_16x16x32_bf16 v[50:53], v[160:163], v[184:187], v[50:53]
	v_mfma_f32_16x16x32_bf16 v[42:45], v[168:171], v[184:187], v[42:45]
	v_mfma_f32_16x16x32_bf16 v[34:37], v[160:163], v[192:195], v[34:37]
	v_mfma_f32_16x16x32_bf16 v[26:29], v[168:171], v[192:195], v[26:29]
	v_mfma_f32_16x16x32_bf16 v[18:21], v[160:163], v[204:207], v[18:21]
	v_mfma_f32_16x16x32_bf16 v[10:13], v[168:171], v[204:207], v[10:13]
	v_mfma_f32_16x16x32_bf16 v[6:9], v[160:163], v[212:215], v[6:9]
	v_mfma_f32_16x16x32_bf16 v[2:5], v[168:171], v[212:215], v[2:5]
	v_mfma_f32_16x16x32_bf16 v[50:53], v[164:167], v[188:191], v[50:53]
	v_mfma_f32_16x16x32_bf16 v[42:45], v[180:183], v[188:191], v[42:45]
	v_mfma_f32_16x16x32_bf16 v[34:37], v[164:167], v[200:203], v[34:37]
	v_mfma_f32_16x16x32_bf16 v[26:29], v[180:183], v[200:203], v[26:29]
	v_mfma_f32_16x16x32_bf16 v[18:21], v[164:167], v[208:211], v[18:21]
	v_mfma_f32_16x16x32_bf16 v[10:13], v[180:183], v[208:211], v[10:13]
	v_mfma_f32_16x16x32_bf16 v[6:9], v[164:167], v[216:219], v[6:9]
	v_mfma_f32_16x16x32_bf16 v[2:5], v[180:183], v[216:219], v[2:5]
	s_setprio 0
	s_barrier
	s_cbranch_scc0 .LBB0_91
	s_and_b64 vcc, exec, s[46:47]
	s_cbranch_vccz .LBB0_94
	s_barrier

; #define PG8_STAGE(bufoff, gbase, voff) do { _Pragma("unroll") for (int _i = 0; _i < 2; ++_i) \
;         __builtin_amdgcn_global_load_lds((const unsigned*)((const char*)(gbase) + (voff)[_i]), (LAS unsigned*)(lds + (bufoff) + ldsw + _i * 8192), 16, 0, 0); } while (0)
; #define PG8_LDA(dst, b, h) do { _Pragma("unroll") for (int m = 0; m < 4; ++m) _Pragma("unroll") for (int k = 0; k < 2; ++k) dst[m][k] = *(const LAS bf16x8*)(lds + PG8_SA(b, h) + aoff + m * 2048 + k * 1024); } while (0)
; #define PG8_LDB(dst, b, h) do { _Pragma("unroll") for (int n = 0; n < 2; ++n) _Pragma("unroll") for (int k = 0; k < 2; ++k) dst[n][k] = *(const LAS bf16x8*)(lds + PG8_SB(b, h) + boff + n * 2048 + k * 1024); } while (0)
; #define PG8_MMA(ai, bj, At, Bt) do { __builtin_amdgcn_s_setprio(1); _Pragma("unroll") for (int m = 0; m < 4; ++m) _Pragma("unroll") for (int n = 0; n < 2; ++n) _Pragma("unroll") for (int k = 0; k < 2; ++k) \
;         acc[ai][bj][m][n] = __builtin_amdgcn_mfma_f32_16x16x32_bf16(Bt[n][k], At[m][k], acc[ai][bj][m][n], 0, 0, 0); __builtin_amdgcn_s_setprio(0); } while (0)
; #define PG8_WAIT_V(n) asm volatile("s_waitcnt vmcnt(" #n ")" ::: "memory")
; #define PG8_WAIT_L(n) asm volatile("s_waitcnt lgkmcnt(" #n ")" ::: "memory")
; #define PG8_BAR __builtin_amdgcn_s_barrier()
; #define PG8_SCHED __builtin_amdgcn_sched_barrier(0)
; template <class Epi, class Sched>
; __device__ __forceinline__ void gemm_phase(LAS unsigned char* lds, const int lda, const int ldb, const int K, const Sched& S, const Epi& E, int tid) {
;     ...
;         for (int t = 0; t < nt; t += 2) {
;             const bool last = (t == nt - 2);
;             const char* a1 = cA + (size_t)(t + 1) * kstep;
;             const char* a2 = last ? nA : cA + (size_t)(t + 2) * kstep; const char* b2 = last ? nB : cB + (size_t)(t + 2) * kstep;
;             const char* a3 = a2 + kstep; const char* b3 = b2 + kstep;
;             PG8_LDB(B0, 0, 0); PG8_LDB(B1, 0, 1); PG8_SCHED; PG8_LDA(At, 0, 0); PG8_STAGE(PG8_SA(1, 1), a1 + hA, voffA);
;             PG8_WAIT_V(8); PG8_WAIT_L(0); PG8_BAR; PG8_MMA(0, 0, At, B0); PG8_MMA(0, 1, At, B1); PG8_BAR; PG8_SCHED;
;             PG8_LDA(At, 0, 1); PG8_STAGE(PG8_SB(0, 0), b2, voffB); PG8_STAGE(PG8_SB(0, 1), b2 + hB, voffB); PG8_STAGE(PG8_SA(0, 0), a2, voffA);
;             PG8_WAIT_V(8); PG8_WAIT_L(0); PG8_BAR; PG8_MMA(1, 0, At, B0); PG8_MMA(1, 1, At, B1); PG8_BAR; PG8_SCHED;
.LBB0_262:
	s_add_u32 s10, s8, 0xfff80080
	s_addc_u32 s11, s9, -1
	s_add_i32 s34, 0, 0x10000
	s_cmp_eq_u32 s43, 28
	s_cselect_b32 s15, s5, s11
	s_cselect_b32 s14, s4, s10
	s_cselect_b32 s11, s7, s42
	s_cselect_b32 s10, s6, s33
	s_add_i32 s35, 0, 0x14000
	v_add_u32_e32 v160, s34, v145
	v_add_u32_e32 v176, s35, v145
	ds_read_b128 v[148:151], v160
	ds_read_b128 v[152:155], v160 offset:1024
	ds_read_b128 v[156:159], v160 offset:2048
	ds_read_b128 v[160:163], v160 offset:3072
	ds_read_b128 v[164:167], v176
	ds_read_b128 v[168:171], v176 offset:1024
	ds_read_b128 v[172:175], v176 offset:2048
	ds_read_b128 v[176:179], v176 offset:3072
	s_add_i32 m0, s17, 0xc000
	ds_read_b128 v[180:183], v147
	ds_read_b128 v[184:187], v147 offset:1024
	ds_read_b128 v[188:191], v147 offset:2048
	ds_read_b128 v[192:195], v147 offset:3072
	ds_read_b128 v[200:203], v147 offset:4096
	ds_read_b128 v[204:207], v147 offset:5120
	ds_read_b128 v[208:211], v147 offset:6144
	ds_read_b128 v[212:215], v147 offset:7168
	global_load_lds_dwordx4 v140, s[8:9]
	s_add_i32 m0, s17, 0xe000
	s_nop 0
	global_load_lds_dwordx4 v142, s[8:9]
	s_waitcnt vmcnt(8)
	s_waitcnt lgkmcnt(0)
	s_barrier
	s_setprio 1
	v_mfma_f32_16x16x32_bf16 v[126:129], v[148:151], v[180:183], v[126:129]
	v_mfma_f32_16x16x32_bf16 v[122:125], v[156:159], v[180:183], v[122:125]
	v_mfma_f32_16x16x32_bf16 v[118:121], v[148:151], v[188:191], v[118:121]
	v_mfma_f32_16x16x32_bf16 v[114:117], v[156:159], v[188:191], v[114:117]
	v_mfma_f32_16x16x32_bf16 v[110:113], v[148:151], v[200:203], v[110:113]
	v_mfma_f32_16x16x32_bf16 v[102:105], v[156:159], v[200:203], v[102:105]
	v_mfma_f32_16x16x32_bf16 v[94:97], v[148:151], v[208:211], v[94:97]
	v_mfma_f32_16x16x32_bf16 v[86:89], v[156:159], v[208:211], v[86:89]
	v_mfma_f32_16x16x32_bf16 v[126:129], v[152:155], v[184:187], v[126:129]
	v_mfma_f32_16x16x32_bf16 v[122:125], v[160:163], v[184:187], v[122:125]
	v_mfma_f32_16x16x32_bf16 v[118:121], v[152:155], v[192:195], v[118:121]
	v_mfma_f32_16x16x32_bf16 v[114:117], v[160:163], v[192:195], v[114:117]
	v_mfma_f32_16x16x32_bf16 v[110:113], v[152:155], v[204:207], v[110:113]
	v_mfma_f32_16x16x32_bf16 v[102:105], v[160:163], v[204:207], v[102:105]
	v_mfma_f32_16x16x32_bf16 v[94:97], v[152:155], v[212:215], v[94:97]
	v_mfma_f32_16x16x32_bf16 v[86:89], v[160:163], v[212:215], v[86:89]
	s_setprio 0
	s_setprio 1
	v_mfma_f32_16x16x32_bf16 v[106:109], v[164:167], v[180:183], v[106:109]
	v_mfma_f32_16x16x32_bf16 v[98:101], v[172:175], v[180:183], v[98:101]
	v_mfma_f32_16x16x32_bf16 v[90:93], v[164:167], v[188:191], v[90:93]
	v_mfma_f32_16x16x32_bf16 v[82:85], v[172:175], v[188:191], v[82:85]
	v_mfma_f32_16x16x32_bf16 v[78:81], v[164:167], v[200:203], v[78:81]
	v_mfma_f32_16x16x32_bf16 v[74:77], v[172:175], v[200:203], v[74:77]
	v_mfma_f32_16x16x32_bf16 v[70:73], v[164:167], v[208:211], v[70:73]
	v_mfma_f32_16x16x32_bf16 v[66:69], v[172:175], v[208:211], v[66:69]
	v_mfma_f32_16x16x32_bf16 v[106:109], v[168:171], v[184:187], v[106:109]
	v_mfma_f32_16x16x32_bf16 v[98:101], v[176:179], v[184:187], v[98:101]
	v_mfma_f32_16x16x32_bf16 v[90:93], v[168:171], v[192:195], v[90:93]
	v_mfma_f32_16x16x32_bf16 v[82:85], v[176:179], v[192:195], v[82:85]
	v_mfma_f32_16x16x32_bf16 v[78:81], v[168:171], v[204:207], v[78:81]
	v_mfma_f32_16x16x32_bf16 v[74:77], v[176:179], v[204:207], v[74:77]
	v_mfma_f32_16x16x32_bf16 v[70:73], v[168:171], v[212:215], v[70:73]
	v_mfma_f32_16x16x32_bf16 v[66:69], v[176:179], v[212:215], v[66:69]
	s_setprio 0
	s_barrier
	s_add_u32 s98, s10, s30
	s_addc_u32 s99, s11, s31
	s_add_u32 s100, s14, s30
	s_addc_u32 s101, s15, s31
	s_add_i32 s34, s34, s16
	s_mov_b32 m0, s34
	ds_read_b128 v[180:183], v147 offset:16384
	ds_read_b128 v[184:187], v147 offset:17408
	ds_read_b128 v[188:191], v147 offset:18432
	ds_read_b128 v[192:195], v147 offset:19456
	ds_read_b128 v[200:203], v147 offset:20480
	ds_read_b128 v[204:207], v147 offset:21504
	ds_read_b128 v[208:211], v147 offset:22528
	ds_read_b128 v[212:215], v147 offset:23552
	global_load_lds_dwordx4 v132, s[10:11]
	s_add_i32 m0, s34, 0x2000
	s_add_u32 s44, s10, 0x80000
	s_addc_u32 s45, s11, 0
	s_add_i32 s34, s35, s16
	global_load_lds_dwordx4 v136, s[10:11]
	s_mov_b32 m0, s34
	s_nop 0
	global_load_lds_dwordx4 v132, s[44:45]
	s_add_i32 m0, s34, 0x2000
	s_nop 0
	global_load_lds_dwordx4 v136, s[44:45]
	s_mov_b32 m0, s17
	s_nop 0
	global_load_lds_dwordx4 v130, s[14:15]
	s_mov_b32 m0, s18
	s_nop 0
	global_load_lds_dwordx4 v134, s[14:15]
	s_waitcnt vmcnt(8)
	s_waitcnt lgkmcnt(0)
	s_barrier
	s_setprio 1
	v_mfma_f32_16x16x32_bf16 v[62:65], v[148:151], v[180:183], v[62:65]
	v_mfma_f32_16x16x32_bf16 v[58:61], v[156:159], v[180:183], v[58:61]
	v_mfma_f32_16x16x32_bf16 v[54:57], v[148:151], v[188:191], v[54:57]
	v_mfma_f32_16x16x32_bf16 v[50:53], v[156:159], v[188:191], v[50:53]
	v_mfma_f32_16x16x32_bf16 v[46:49], v[148:151], v[200:203], v[46:49]
	v_mfma_f32_16x16x32_bf16 v[38:41], v[156:159], v[200:203], v[38:41]
	v_mfma_f32_16x16x32_bf16 v[30:33], v[148:151], v[208:211], v[30:33]
	v_mfma_f32_16x16x32_bf16 v[22:25], v[156:159], v[208:211], v[22:25]
	v_mfma_f32_16x16x32_bf16 v[62:65], v[152:155], v[184:187], v[62:65]
	v_mfma_f32_16x16x32_bf16 v[58:61], v[160:163], v[184:187], v[58:61]
	v_mfma_f32_16x16x32_bf16 v[54:57], v[152:155], v[192:195], v[54:57]
	v_mfma_f32_16x16x32_bf16 v[50:53], v[160:163], v[192:195], v[50:53]
	v_mfma_f32_16x16x32_bf16 v[46:49], v[152:155], v[204:207], v[46:49]
	v_mfma_f32_16x16x32_bf16 v[38:41], v[160:163], v[204:207], v[38:41]
	v_mfma_f32_16x16x32_bf16 v[30:33], v[152:155], v[212:215], v[30:33]
	v_mfma_f32_16x16x32_bf16 v[22:25], v[160:163], v[212:215], v[22:25]
	s_setprio 0
	s_setprio 1
	v_mfma_f32_16x16x32_bf16 v[42:45], v[164:167], v[180:183], v[42:45]
	v_mfma_f32_16x16x32_bf16 v[34:37], v[172:175], v[180:183], v[34:37]
	v_mfma_f32_16x16x32_bf16 v[26:29], v[164:167], v[188:191], v[26:29]
	v_mfma_f32_16x16x32_bf16 v[18:21], v[172:175], v[188:191], v[18:21]
	v_mfma_f32_16x16x32_bf16 v[14:17], v[164:167], v[200:203], v[14:17]
	v_mfma_f32_16x16x32_bf16 v[10:13], v[172:175], v[200:203], v[10:13]
	v_mfma_f32_16x16x32_bf16 v[6:9], v[164:167], v[208:211], v[6:9]
	v_mfma_f32_16x16x32_bf16 v[2:5], v[172:175], v[208:211], v[2:5]
	v_mfma_f32_16x16x32_bf16 v[42:45], v[168:171], v[184:187], v[42:45]
	v_mfma_f32_16x16x32_bf16 v[34:37], v[176:179], v[184:187], v[34:37]
	v_mfma_f32_16x16x32_bf16 v[26:29], v[168:171], v[192:195], v[26:29]
	v_mfma_f32_16x16x32_bf16 v[18:21], v[176:179], v[192:195], v[18:21]
	v_mfma_f32_16x16x32_bf16 v[14:17], v[168:171], v[204:207], v[14:17]
	v_mfma_f32_16x16x32_bf16 v[10:13], v[176:179], v[204:207], v[10:13]
	v_mfma_f32_16x16x32_bf16 v[6:9], v[168:171], v[212:215], v[6:9]
	v_mfma_f32_16x16x32_bf16 v[2:5], v[176:179], v[212:215], v[2:5]
	s_setprio 0
	s_barrier
; #define PG8_STAGE(bufoff, gbase, voff) do { _Pragma("unroll") for (int _i = 0; _i < 2; ++_i) \
;         __builtin_amdgcn_global_load_lds((const unsigned*)((const char*)(gbase) + (voff)[_i]), (LAS unsigned*)(lds + (bufoff) + ldsw + _i * 8192), 16, 0, 0); } while (0)
; #define PG8_LDA(dst, b, h) do { _Pragma("unroll") for (int m = 0; m < 4; ++m) _Pragma("unroll") for (int k = 0; k < 2; ++k) dst[m][k] = *(const LAS bf16x8*)(lds + PG8_SA(b, h) + aoff + m * 2048 + k * 1024); } while (0)
; #define PG8_LDB(dst, b, h) do { _Pragma("unroll") for (int n = 0; n < 2; ++n) _Pragma("unroll") for (int k = 0; k < 2; ++k) dst[n][k] = *(const LAS bf16x8*)(lds + PG8_SB(b, h) + boff + n * 2048 + k * 1024); } while (0)
; #define PG8_MMA(ai, bj, At, Bt) do { __builtin_amdgcn_s_setprio(1); _Pragma("unroll") for (int m = 0; m < 4; ++m) _Pragma("unroll") for (int n = 0; n < 2; ++n) _Pragma("unroll") for (int k = 0; k < 2; ++k) \
;         acc[ai][bj][m][n] = __builtin_amdgcn_mfma_f32_16x16x32_bf16(Bt[n][k], At[m][k], acc[ai][bj][m][n], 0, 0, 0); __builtin_amdgcn_s_setprio(0); } while (0)
; #define PG8_WAIT_V(n) asm volatile("s_waitcnt vmcnt(" #n ")" ::: "memory")
; #define PG8_WAIT_L(n) asm volatile("s_waitcnt lgkmcnt(" #n ")" ::: "memory")
; #define PG8_BAR __builtin_amdgcn_s_barrier()
; #define PG8_SCHED __builtin_amdgcn_sched_barrier(0)
; template <class Epi, class Sched>
; __device__ __forceinline__ void gemm_phase(LAS unsigned char* lds, const int lda, const int ldb, const int K, const Sched& S, const Epi& E, int tid) {
;     ...
;             PG8_LDB(B0, 1, 0); PG8_LDB(B1, 1, 1); PG8_SCHED; PG8_LDA(At, 1, 0); PG8_STAGE(PG8_SA(0, 1), a2 + hA, voffA);
;             PG8_WAIT_V(8); PG8_WAIT_L(0); PG8_BAR; PG8_MMA(0, 0, At, B0); PG8_MMA(0, 1, At, B1); PG8_BAR; PG8_SCHED;
;             PG8_LDA(At, 1, 1); PG8_STAGE(PG8_SB(1, 0), b3, voffB); PG8_STAGE(PG8_SB(1, 1), b3 + hB, voffB); PG8_STAGE(PG8_SA(1, 0), a3, voffA);
;             PG8_WAIT_V(8); PG8_WAIT_L(0); PG8_BAR; PG8_MMA(1, 0, At, B0); PG8_MMA(1, 1, At, B1); PG8_BAR; PG8_SCHED;
;         }
;         if (wr == 0) PG8_BAR;
	s_add_i32 s34, 0, 0x18000
	s_add_i32 s35, 0, 0x1c000
	v_add_u32_e32 v160, s34, v145
	v_add_u32_e32 v176, s35, v145
	ds_read_b128 v[148:151], v160
	ds_read_b128 v[152:155], v160 offset:1024
	ds_read_b128 v[156:159], v160 offset:2048
	ds_read_b128 v[160:163], v160 offset:3072
	ds_read_b128 v[164:167], v176
	ds_read_b128 v[168:171], v176 offset:1024
	ds_read_b128 v[172:175], v176 offset:2048
	ds_read_b128 v[176:179], v176 offset:3072
	s_add_u32 s14, s14, 0x80000
	s_addc_u32 s15, s15, 0
	s_mov_b32 m0, s19
	ds_read_b128 v[180:183], v147 offset:32768
	ds_read_b128 v[184:187], v147 offset:33792
	ds_read_b128 v[188:191], v147 offset:34816
	ds_read_b128 v[192:195], v147 offset:35840
	ds_read_b128 v[200:203], v147 offset:36864
	ds_read_b128 v[204:207], v147 offset:37888
	ds_read_b128 v[208:211], v147 offset:38912
	ds_read_b128 v[212:215], v147 offset:39936
	global_load_lds_dwordx4 v130, s[14:15]
	s_mov_b32 m0, s20
	s_nop 0
	global_load_lds_dwordx4 v134, s[14:15]
	s_waitcnt vmcnt(8)
	s_waitcnt lgkmcnt(0)
	s_barrier
	s_setprio 1
	v_mfma_f32_16x16x32_bf16 v[126:129], v[148:151], v[180:183], v[126:129]
	v_mfma_f32_16x16x32_bf16 v[122:125], v[156:159], v[180:183], v[122:125]
	v_mfma_f32_16x16x32_bf16 v[118:121], v[148:151], v[188:191], v[118:121]
	v_mfma_f32_16x16x32_bf16 v[114:117], v[156:159], v[188:191], v[114:117]
	v_mfma_f32_16x16x32_bf16 v[110:113], v[148:151], v[200:203], v[110:113]
	v_mfma_f32_16x16x32_bf16 v[102:105], v[156:159], v[200:203], v[102:105]
	v_mfma_f32_16x16x32_bf16 v[94:97], v[148:151], v[208:211], v[94:97]
	v_mfma_f32_16x16x32_bf16 v[86:89], v[156:159], v[208:211], v[86:89]
	v_mfma_f32_16x16x32_bf16 v[126:129], v[152:155], v[184:187], v[126:129]
	v_mfma_f32_16x16x32_bf16 v[122:125], v[160:163], v[184:187], v[122:125]
	v_mfma_f32_16x16x32_bf16 v[118:121], v[152:155], v[192:195], v[118:121]
	v_mfma_f32_16x16x32_bf16 v[114:117], v[160:163], v[192:195], v[114:117]
	v_mfma_f32_16x16x32_bf16 v[110:113], v[152:155], v[204:207], v[110:113]
	v_mfma_f32_16x16x32_bf16 v[102:105], v[160:163], v[204:207], v[102:105]
	v_mfma_f32_16x16x32_bf16 v[94:97], v[152:155], v[212:215], v[94:97]
	v_mfma_f32_16x16x32_bf16 v[86:89], v[160:163], v[212:215], v[86:89]
	s_setprio 0
	s_setprio 1
	v_mfma_f32_16x16x32_bf16 v[106:109], v[164:167], v[180:183], v[106:109]
	v_mfma_f32_16x16x32_bf16 v[98:101], v[172:175], v[180:183], v[98:101]
	v_mfma_f32_16x16x32_bf16 v[90:93], v[164:167], v[188:191], v[90:93]
	v_mfma_f32_16x16x32_bf16 v[82:85], v[172:175], v[188:191], v[82:85]
	v_mfma_f32_16x16x32_bf16 v[78:81], v[164:167], v[200:203], v[78:81]
	v_mfma_f32_16x16x32_bf16 v[74:77], v[172:175], v[200:203], v[74:77]
	v_mfma_f32_16x16x32_bf16 v[70:73], v[164:167], v[208:211], v[70:73]
	v_mfma_f32_16x16x32_bf16 v[66:69], v[172:175], v[208:211], v[66:69]
	v_mfma_f32_16x16x32_bf16 v[106:109], v[168:171], v[184:187], v[106:109]
	v_mfma_f32_16x16x32_bf16 v[98:101], v[176:179], v[184:187], v[98:101]
	v_mfma_f32_16x16x32_bf16 v[90:93], v[168:171], v[192:195], v[90:93]
	v_mfma_f32_16x16x32_bf16 v[82:85], v[176:179], v[192:195], v[82:85]
	v_mfma_f32_16x16x32_bf16 v[78:81], v[168:171], v[204:207], v[78:81]
	v_mfma_f32_16x16x32_bf16 v[74:77], v[176:179], v[204:207], v[74:77]
	v_mfma_f32_16x16x32_bf16 v[70:73], v[168:171], v[212:215], v[70:73]
	v_mfma_f32_16x16x32_bf16 v[66:69], v[176:179], v[212:215], v[66:69]
	s_setprio 0
	s_barrier
	s_add_i32 s14, s34, s16
	s_mov_b32 m0, s14
	ds_read_b128 v[180:183], v147 offset:49152
	ds_read_b128 v[184:187], v147 offset:50176
	ds_read_b128 v[188:191], v147 offset:51200
	ds_read_b128 v[192:195], v147 offset:52224
	ds_read_b128 v[200:203], v147 offset:53248
	ds_read_b128 v[204:207], v147 offset:54272
	ds_read_b128 v[208:211], v147 offset:55296
	ds_read_b128 v[212:215], v147 offset:56320
	global_load_lds_dwordx4 v132, s[98:99]
	s_add_i32 m0, s14, 0x2000
	s_add_u32 s10, s10, 0x80080
	s_addc_u32 s11, s11, 0
	s_add_i32 s14, s35, s16
	global_load_lds_dwordx4 v136, s[98:99]
	s_mov_b32 m0, s14
	s_nop 0
	global_load_lds_dwordx4 v132, s[10:11]
	s_add_i32 m0, s14, 0x2000
	s_nop 0
	global_load_lds_dwordx4 v136, s[10:11]
	s_mov_b32 m0, s21
	s_nop 0
	global_load_lds_dwordx4 v130, s[100:101]
	s_mov_b32 m0, s22
	s_nop 0
	global_load_lds_dwordx4 v134, s[100:101]
	s_waitcnt vmcnt(8)
	s_waitcnt lgkmcnt(0)
	s_barrier
	s_setprio 1
	s_add_i32 s43, s43, 2
	s_add_u32 s8, s8, 0x100
	s_addc_u32 s9, s9, 0
	s_add_u32 s33, s33, 0x100
	s_addc_u32 s42, s42, 0
	s_cmp_gt_u32 s43, 29
	v_mfma_f32_16x16x32_bf16 v[62:65], v[148:151], v[180:183], v[62:65]
	v_mfma_f32_16x16x32_bf16 v[58:61], v[156:159], v[180:183], v[58:61]
	v_mfma_f32_16x16x32_bf16 v[54:57], v[148:151], v[188:191], v[54:57]
	v_mfma_f32_16x16x32_bf16 v[50:53], v[156:159], v[188:191], v[50:53]
	v_mfma_f32_16x16x32_bf16 v[46:49], v[148:151], v[200:203], v[46:49]
	v_mfma_f32_16x16x32_bf16 v[38:41], v[156:159], v[200:203], v[38:41]
	v_mfma_f32_16x16x32_bf16 v[30:33], v[148:151], v[208:211], v[30:33]
	v_mfma_f32_16x16x32_bf16 v[22:25], v[156:159], v[208:211], v[22:25]
	v_mfma_f32_16x16x32_bf16 v[62:65], v[152:155], v[184:187], v[62:65]
	v_mfma_f32_16x16x32_bf16 v[58:61], v[160:163], v[184:187], v[58:61]
	v_mfma_f32_16x16x32_bf16 v[54:57], v[152:155], v[192:195], v[54:57]
	v_mfma_f32_16x16x32_bf16 v[50:53], v[160:163], v[192:195], v[50:53]
	v_mfma_f32_16x16x32_bf16 v[46:49], v[152:155], v[204:207], v[46:49]
	v_mfma_f32_16x16x32_bf16 v[38:41], v[160:163], v[204:207], v[38:41]
	v_mfma_f32_16x16x32_bf16 v[30:33], v[152:155], v[212:215], v[30:33]
	v_mfma_f32_16x16x32_bf16 v[22:25], v[160:163], v[212:215], v[22:25]
	s_setprio 0
	s_setprio 1
	v_mfma_f32_16x16x32_bf16 v[42:45], v[164:167], v[180:183], v[42:45]
	v_mfma_f32_16x16x32_bf16 v[34:37], v[172:175], v[180:183], v[34:37]
	v_mfma_f32_16x16x32_bf16 v[26:29], v[164:167], v[188:191], v[26:29]
	v_mfma_f32_16x16x32_bf16 v[18:21], v[172:175], v[188:191], v[18:21]
	v_mfma_f32_16x16x32_bf16 v[14:17], v[164:167], v[200:203], v[14:17]
	v_mfma_f32_16x16x32_bf16 v[10:13], v[172:175], v[200:203], v[10:13]
	v_mfma_f32_16x16x32_bf16 v[6:9], v[164:167], v[208:211], v[6:9]
	v_mfma_f32_16x16x32_bf16 v[2:5], v[172:175], v[208:211], v[2:5]
	v_mfma_f32_16x16x32_bf16 v[42:45], v[168:171], v[184:187], v[42:45]
	v_mfma_f32_16x16x32_bf16 v[34:37], v[176:179], v[184:187], v[34:37]
	v_mfma_f32_16x16x32_bf16 v[26:29], v[168:171], v[192:195], v[26:29]
	v_mfma_f32_16x16x32_bf16 v[18:21], v[176:179], v[192:195], v[18:21]
	v_mfma_f32_16x16x32_bf16 v[14:17], v[168:171], v[204:207], v[14:17]
	v_mfma_f32_16x16x32_bf16 v[10:13], v[176:179], v[204:207], v[10:13]
	v_mfma_f32_16x16x32_bf16 v[6:9], v[168:171], v[212:215], v[6:9]
	v_mfma_f32_16x16x32_bf16 v[2:5], v[176:179], v[212:215], v[2:5]
	s_setprio 0
	s_barrier
	s_cbranch_scc0 .LBB0_262
	s_and_b64 vcc, exec, s[2:3]
	s_cbranch_vccz .LBB0_265
	s_barrier

; #define PG8_STAGE(bufoff, gbase, voff) do { _Pragma("unroll") for (int _i = 0; _i < 2; ++_i) \
;         __builtin_amdgcn_global_load_lds((const unsigned*)((const char*)(gbase) + (voff)[_i]), (LAS unsigned*)(lds + (bufoff) + ldsw + _i * 8192), 16, 0, 0); } while (0)
; #define PG8_LDA(dst, b, h) do { _Pragma("unroll") for (int m = 0; m < 4; ++m) _Pragma("unroll") for (int k = 0; k < 2; ++k) dst[m][k] = *(const LAS bf16x8*)(lds + PG8_SA(b, h) + aoff + m * 2048 + k * 1024); } while (0)
; #define PG8_LDB(dst, b, h) do { _Pragma("unroll") for (int n = 0; n < 2; ++n) _Pragma("unroll") for (int k = 0; k < 2; ++k) dst[n][k] = *(const LAS bf16x8*)(lds + PG8_SB(b, h) + boff + n * 2048 + k * 1024); } while (0)
; #define PG8_MMA(ai, bj, At, Bt) do { __builtin_amdgcn_s_setprio(1); _Pragma("unroll") for (int m = 0; m < 4; ++m) _Pragma("unroll") for (int n = 0; n < 2; ++n) _Pragma("unroll") for (int k = 0; k < 2; ++k) \
;         acc[ai][bj][m][n] = __builtin_amdgcn_mfma_f32_16x16x32_bf16(Bt[n][k], At[m][k], acc[ai][bj][m][n], 0, 0, 0); __builtin_amdgcn_s_setprio(0); } while (0)
; #define PG8_WAIT_V(n) asm volatile("s_waitcnt vmcnt(" #n ")" ::: "memory")
; #define PG8_WAIT_L(n) asm volatile("s_waitcnt lgkmcnt(" #n ")" ::: "memory")
; #define PG8_BAR __builtin_amdgcn_s_barrier()
; #define PG8_SCHED __builtin_amdgcn_sched_barrier(0)
; template <class Epi, class Sched>
; __device__ __forceinline__ void gemm_phase(LAS unsigned char* lds, const int lda, const int ldb, const int K, const Sched& S, const Epi& E, int tid) {
;     ...
;         for (int t = 0; t < nt; t += 2) {
;             const bool last = (t == nt - 2);
;             const char* a1 = cA + (size_t)(t + 1) * kstep;
;             const char* a2 = last ? nA : cA + (size_t)(t + 2) * kstep; const char* b2 = last ? nB : cB + (size_t)(t + 2) * kstep;
;             const char* a3 = a2 + kstep; const char* b3 = b2 + kstep;
;             PG8_LDB(B0, 0, 0); PG8_LDB(B1, 0, 1); PG8_SCHED; PG8_LDA(At, 0, 0); PG8_STAGE(PG8_SA(1, 1), a1 + hA, voffA);
;             PG8_WAIT_V(8); PG8_WAIT_L(0); PG8_BAR; PG8_MMA(0, 0, At, B0); PG8_MMA(0, 1, At, B1); PG8_BAR; PG8_SCHED;
;             PG8_LDA(At, 0, 1); PG8_STAGE(PG8_SB(0, 0), b2, voffB); PG8_STAGE(PG8_SB(0, 1), b2 + hB, voffB); PG8_STAGE(PG8_SA(0, 0), a2, voffA);
;             PG8_WAIT_V(8); PG8_WAIT_L(0); PG8_BAR; PG8_MMA(1, 0, At, B0); PG8_MMA(1, 1, At, B1); PG8_BAR; PG8_SCHED;
.LBB0_290:
	s_add_u32 s14, s10, 0xfff80080
	s_addc_u32 s15, s11, -1
	s_add_i32 s34, 0, 0x10000
	s_cmp_eq_u32 s42, 28
	s_cselect_b32 s17, s5, s15
	s_cselect_b32 s16, s4, s14
	s_cselect_b32 s15, s7, s33
	s_cselect_b32 s14, s6, s18
	s_add_i32 s35, 0, 0x14000
	v_add_u32_e32 v156, s34, v163
	v_add_u32_e32 v160, s35, v163
	ds_read_b128 v[144:147], v156
	ds_read_b128 v[148:151], v156 offset:1024
	ds_read_b128 v[152:155], v156 offset:2048
	ds_read_b128 v[156:159], v156 offset:3072
	ds_read_b128 v[166:169], v160
	ds_read_b128 v[170:173], v160 offset:1024
	ds_read_b128 v[174:177], v160 offset:2048
	ds_read_b128 v[178:181], v160 offset:3072
	s_add_i32 m0, s21, 0xc000
	ds_read_b128 v[182:185], v164
	ds_read_b128 v[186:189], v164 offset:1024
	ds_read_b128 v[190:193], v164 offset:2048
	ds_read_b128 v[194:197], v164 offset:3072
	ds_read_b128 v[200:203], v164 offset:4096
	ds_read_b128 v[204:207], v164 offset:5120
	ds_read_b128 v[208:211], v164 offset:6144
	ds_read_b128 v[212:215], v164 offset:7168
	global_load_lds_dwordx4 v140, s[10:11]
	s_add_i32 m0, s21, 0xe000
	s_nop 0
	global_load_lds_dwordx4 v142, s[10:11]
	s_waitcnt vmcnt(8)
	s_waitcnt lgkmcnt(0)
	s_barrier
	s_setprio 1
	v_mfma_f32_16x16x32_bf16 v[126:129], v[144:147], v[182:185], v[126:129]
	v_mfma_f32_16x16x32_bf16 v[122:125], v[152:155], v[182:185], v[122:125]
	v_mfma_f32_16x16x32_bf16 v[118:121], v[144:147], v[190:193], v[118:121]
	v_mfma_f32_16x16x32_bf16 v[114:117], v[152:155], v[190:193], v[114:117]
	v_mfma_f32_16x16x32_bf16 v[102:105], v[144:147], v[200:203], v[102:105]
	v_mfma_f32_16x16x32_bf16 v[98:101], v[152:155], v[200:203], v[98:101]
	v_mfma_f32_16x16x32_bf16 v[86:89], v[144:147], v[208:211], v[86:89]
	v_mfma_f32_16x16x32_bf16 v[82:85], v[152:155], v[208:211], v[82:85]
	v_mfma_f32_16x16x32_bf16 v[126:129], v[148:151], v[186:189], v[126:129]
	v_mfma_f32_16x16x32_bf16 v[122:125], v[156:159], v[186:189], v[122:125]
	v_mfma_f32_16x16x32_bf16 v[118:121], v[148:151], v[194:197], v[118:121]
	v_mfma_f32_16x16x32_bf16 v[114:117], v[156:159], v[194:197], v[114:117]
	v_mfma_f32_16x16x32_bf16 v[102:105], v[148:151], v[204:207], v[102:105]
	v_mfma_f32_16x16x32_bf16 v[98:101], v[156:159], v[204:207], v[98:101]
	v_mfma_f32_16x16x32_bf16 v[86:89], v[148:151], v[212:215], v[86:89]
	v_mfma_f32_16x16x32_bf16 v[82:85], v[156:159], v[212:215], v[82:85]
	s_setprio 0
	s_setprio 1
	v_mfma_f32_16x16x32_bf16 v[110:113], v[166:169], v[182:185], v[110:113]
	v_mfma_f32_16x16x32_bf16 v[106:109], v[174:177], v[182:185], v[106:109]
	v_mfma_f32_16x16x32_bf16 v[94:97], v[166:169], v[190:193], v[94:97]
	v_mfma_f32_16x16x32_bf16 v[90:93], v[174:177], v[190:193], v[90:93]
	v_mfma_f32_16x16x32_bf16 v[78:81], v[166:169], v[200:203], v[78:81]
	v_mfma_f32_16x16x32_bf16 v[74:77], v[174:177], v[200:203], v[74:77]
	v_mfma_f32_16x16x32_bf16 v[70:73], v[166:169], v[208:211], v[70:73]
	v_mfma_f32_16x16x32_bf16 v[66:69], v[174:177], v[208:211], v[66:69]
	v_mfma_f32_16x16x32_bf16 v[110:113], v[170:173], v[186:189], v[110:113]
	v_mfma_f32_16x16x32_bf16 v[106:109], v[178:181], v[186:189], v[106:109]
	v_mfma_f32_16x16x32_bf16 v[94:97], v[170:173], v[194:197], v[94:97]
	v_mfma_f32_16x16x32_bf16 v[90:93], v[178:181], v[194:197], v[90:93]
	v_mfma_f32_16x16x32_bf16 v[78:81], v[170:173], v[204:207], v[78:81]
	v_mfma_f32_16x16x32_bf16 v[74:77], v[178:181], v[204:207], v[74:77]
	v_mfma_f32_16x16x32_bf16 v[70:73], v[170:173], v[212:215], v[70:73]
	v_mfma_f32_16x16x32_bf16 v[66:69], v[178:181], v[212:215], v[66:69]
	s_setprio 0
	s_barrier
	s_add_u32 s98, s14, s30
	s_addc_u32 s99, s15, s31
	s_add_u32 s100, s16, s30
	s_addc_u32 s101, s17, s31
	s_add_i32 s34, s34, s20
	s_mov_b32 m0, s34
	ds_read_b128 v[182:185], v164 offset:16384
	ds_read_b128 v[186:189], v164 offset:17408
	ds_read_b128 v[190:193], v164 offset:18432
	ds_read_b128 v[194:197], v164 offset:19456
	ds_read_b128 v[200:203], v164 offset:20480
	ds_read_b128 v[204:207], v164 offset:21504
	ds_read_b128 v[208:211], v164 offset:22528
	ds_read_b128 v[212:215], v164 offset:23552
	global_load_lds_dwordx4 v0, s[14:15]
	s_add_i32 m0, s34, 0x2000
	s_add_u32 s44, s14, 0x80000
	s_addc_u32 s45, s15, 0
	s_add_i32 s34, s35, s20
	global_load_lds_dwordx4 v134, s[14:15]
	s_mov_b32 m0, s34
	s_nop 0
	global_load_lds_dwordx4 v0, s[44:45]
	s_add_i32 m0, s34, 0x2000
	s_nop 0
	global_load_lds_dwordx4 v134, s[44:45]
	s_mov_b32 m0, s21
	s_nop 0
	global_load_lds_dwordx4 v130, s[16:17]
	s_mov_b32 m0, s22
	s_nop 0
	global_load_lds_dwordx4 v132, s[16:17]
	s_waitcnt vmcnt(8)
	s_waitcnt lgkmcnt(0)
	s_barrier
	s_setprio 1
	v_mfma_f32_16x16x32_bf16 v[62:65], v[144:147], v[182:185], v[62:65]
	v_mfma_f32_16x16x32_bf16 v[58:61], v[152:155], v[182:185], v[58:61]
	v_mfma_f32_16x16x32_bf16 v[54:57], v[144:147], v[190:193], v[54:57]
	v_mfma_f32_16x16x32_bf16 v[50:53], v[152:155], v[190:193], v[50:53]
	v_mfma_f32_16x16x32_bf16 v[38:41], v[144:147], v[200:203], v[38:41]
	v_mfma_f32_16x16x32_bf16 v[34:37], v[152:155], v[200:203], v[34:37]
	v_mfma_f32_16x16x32_bf16 v[22:25], v[144:147], v[208:211], v[22:25]
	v_mfma_f32_16x16x32_bf16 v[18:21], v[152:155], v[208:211], v[18:21]
	v_mfma_f32_16x16x32_bf16 v[62:65], v[148:151], v[186:189], v[62:65]
	v_mfma_f32_16x16x32_bf16 v[58:61], v[156:159], v[186:189], v[58:61]
	v_mfma_f32_16x16x32_bf16 v[54:57], v[148:151], v[194:197], v[54:57]
	v_mfma_f32_16x16x32_bf16 v[50:53], v[156:159], v[194:197], v[50:53]
	v_mfma_f32_16x16x32_bf16 v[38:41], v[148:151], v[204:207], v[38:41]
	v_mfma_f32_16x16x32_bf16 v[34:37], v[156:159], v[204:207], v[34:37]
	v_mfma_f32_16x16x32_bf16 v[22:25], v[148:151], v[212:215], v[22:25]
	v_mfma_f32_16x16x32_bf16 v[18:21], v[156:159], v[212:215], v[18:21]
	s_setprio 0
	s_setprio 1
	v_mfma_f32_16x16x32_bf16 v[46:49], v[166:169], v[182:185], v[46:49]
	v_mfma_f32_16x16x32_bf16 v[42:45], v[174:177], v[182:185], v[42:45]
	v_mfma_f32_16x16x32_bf16 v[30:33], v[166:169], v[190:193], v[30:33]
	v_mfma_f32_16x16x32_bf16 v[26:29], v[174:177], v[190:193], v[26:29]
	v_mfma_f32_16x16x32_bf16 v[14:17], v[166:169], v[200:203], v[14:17]
	v_mfma_f32_16x16x32_bf16 v[10:13], v[174:177], v[200:203], v[10:13]
	v_mfma_f32_16x16x32_bf16 v[6:9], v[166:169], v[208:211], v[6:9]
	v_mfma_f32_16x16x32_bf16 v[2:5], v[174:177], v[208:211], v[2:5]
	v_mfma_f32_16x16x32_bf16 v[46:49], v[170:173], v[186:189], v[46:49]
	v_mfma_f32_16x16x32_bf16 v[42:45], v[178:181], v[186:189], v[42:45]
	v_mfma_f32_16x16x32_bf16 v[30:33], v[170:173], v[194:197], v[30:33]
	v_mfma_f32_16x16x32_bf16 v[26:29], v[178:181], v[194:197], v[26:29]
	v_mfma_f32_16x16x32_bf16 v[14:17], v[170:173], v[204:207], v[14:17]
	v_mfma_f32_16x16x32_bf16 v[10:13], v[178:181], v[204:207], v[10:13]
	v_mfma_f32_16x16x32_bf16 v[6:9], v[170:173], v[212:215], v[6:9]
	v_mfma_f32_16x16x32_bf16 v[2:5], v[178:181], v[212:215], v[2:5]
	s_setprio 0
	s_barrier
; #define PG8_STAGE(bufoff, gbase, voff) do { _Pragma("unroll") for (int _i = 0; _i < 2; ++_i) \
;         __builtin_amdgcn_global_load_lds((const unsigned*)((const char*)(gbase) + (voff)[_i]), (LAS unsigned*)(lds + (bufoff) + ldsw + _i * 8192), 16, 0, 0); } while (0)
; #define PG8_LDA(dst, b, h) do { _Pragma("unroll") for (int m = 0; m < 4; ++m) _Pragma("unroll") for (int k = 0; k < 2; ++k) dst[m][k] = *(const LAS bf16x8*)(lds + PG8_SA(b, h) + aoff + m * 2048 + k * 1024); } while (0)
; #define PG8_LDB(dst, b, h) do { _Pragma("unroll") for (int n = 0; n < 2; ++n) _Pragma("unroll") for (int k = 0; k < 2; ++k) dst[n][k] = *(const LAS bf16x8*)(lds + PG8_SB(b, h) + boff + n * 2048 + k * 1024); } while (0)
; #define PG8_MMA(ai, bj, At, Bt) do { __builtin_amdgcn_s_setprio(1); _Pragma("unroll") for (int m = 0; m < 4; ++m) _Pragma("unroll") for (int n = 0; n < 2; ++n) _Pragma("unroll") for (int k = 0; k < 2; ++k) \
;         acc[ai][bj][m][n] = __builtin_amdgcn_mfma_f32_16x16x32_bf16(Bt[n][k], At[m][k], acc[ai][bj][m][n], 0, 0, 0); __builtin_amdgcn_s_setprio(0); } while (0)
; #define PG8_WAIT_V(n) asm volatile("s_waitcnt vmcnt(" #n ")" ::: "memory")
; #define PG8_WAIT_L(n) asm volatile("s_waitcnt lgkmcnt(" #n ")" ::: "memory")
; #define PG8_BAR __builtin_amdgcn_s_barrier()
; #define PG8_SCHED __builtin_amdgcn_sched_barrier(0)
; template <class Epi, class Sched>
; __device__ __forceinline__ void gemm_phase(LAS unsigned char* lds, const int lda, const int ldb, const int K, const Sched& S, const Epi& E, int tid) {
;     ...
;             PG8_LDB(B0, 1, 0); PG8_LDB(B1, 1, 1); PG8_SCHED; PG8_LDA(At, 1, 0); PG8_STAGE(PG8_SA(0, 1), a2 + hA, voffA);
;             PG8_WAIT_V(8); PG8_WAIT_L(0); PG8_BAR; PG8_MMA(0, 0, At, B0); PG8_MMA(0, 1, At, B1); PG8_BAR; PG8_SCHED;
;             PG8_LDA(At, 1, 1); PG8_STAGE(PG8_SB(1, 0), b3, voffB); PG8_STAGE(PG8_SB(1, 1), b3 + hB, voffB); PG8_STAGE(PG8_SA(1, 0), a3, voffA);
;             PG8_WAIT_V(8); PG8_WAIT_L(0); PG8_BAR; PG8_MMA(1, 0, At, B0); PG8_MMA(1, 1, At, B1); PG8_BAR; PG8_SCHED;
;         }
;         if (wr == 0) PG8_BAR;
	s_add_i32 s34, 0, 0x18000
	s_add_i32 s35, 0, 0x1c000
	v_add_u32_e32 v156, s34, v163
	v_add_u32_e32 v165, s35, v163
	ds_read_b128 v[144:147], v156
	ds_read_b128 v[148:151], v156 offset:1024
	ds_read_b128 v[152:155], v156 offset:2048
	ds_read_b128 v[156:159], v156 offset:3072
	ds_read_b128 v[166:169], v165
	ds_read_b128 v[170:173], v165 offset:1024
	ds_read_b128 v[174:177], v165 offset:2048
	ds_read_b128 v[178:181], v165 offset:3072
	s_add_u32 s16, s16, 0x80000
	s_addc_u32 s17, s17, 0
	s_mov_b32 m0, s23
	ds_read_b128 v[182:185], v164 offset:32768
	ds_read_b128 v[186:189], v164 offset:33792
	ds_read_b128 v[190:193], v164 offset:34816
	ds_read_b128 v[194:197], v164 offset:35840
	ds_read_b128 v[200:203], v164 offset:36864
	ds_read_b128 v[204:207], v164 offset:37888
	ds_read_b128 v[208:211], v164 offset:38912
	ds_read_b128 v[212:215], v164 offset:39936
	global_load_lds_dwordx4 v130, s[16:17]
	s_mov_b32 m0, s25
	s_nop 0
	global_load_lds_dwordx4 v132, s[16:17]
	s_waitcnt vmcnt(8)
	s_waitcnt lgkmcnt(0)
	s_barrier
	s_setprio 1
	v_mfma_f32_16x16x32_bf16 v[126:129], v[144:147], v[182:185], v[126:129]
	v_mfma_f32_16x16x32_bf16 v[122:125], v[152:155], v[182:185], v[122:125]
	v_mfma_f32_16x16x32_bf16 v[118:121], v[144:147], v[190:193], v[118:121]
	v_mfma_f32_16x16x32_bf16 v[114:117], v[152:155], v[190:193], v[114:117]
	v_mfma_f32_16x16x32_bf16 v[102:105], v[144:147], v[200:203], v[102:105]
	v_mfma_f32_16x16x32_bf16 v[98:101], v[152:155], v[200:203], v[98:101]
	v_mfma_f32_16x16x32_bf16 v[86:89], v[144:147], v[208:211], v[86:89]
	v_mfma_f32_16x16x32_bf16 v[82:85], v[152:155], v[208:211], v[82:85]
	v_mfma_f32_16x16x32_bf16 v[126:129], v[148:151], v[186:189], v[126:129]
	v_mfma_f32_16x16x32_bf16 v[122:125], v[156:159], v[186:189], v[122:125]
	v_mfma_f32_16x16x32_bf16 v[118:121], v[148:151], v[194:197], v[118:121]
	v_mfma_f32_16x16x32_bf16 v[114:117], v[156:159], v[194:197], v[114:117]
	v_mfma_f32_16x16x32_bf16 v[102:105], v[148:151], v[204:207], v[102:105]
	v_mfma_f32_16x16x32_bf16 v[98:101], v[156:159], v[204:207], v[98:101]
	v_mfma_f32_16x16x32_bf16 v[86:89], v[148:151], v[212:215], v[86:89]
	v_mfma_f32_16x16x32_bf16 v[82:85], v[156:159], v[212:215], v[82:85]
	s_setprio 0
	s_setprio 1
	v_mfma_f32_16x16x32_bf16 v[110:113], v[166:169], v[182:185], v[110:113]
	v_mfma_f32_16x16x32_bf16 v[106:109], v[174:177], v[182:185], v[106:109]
	v_mfma_f32_16x16x32_bf16 v[94:97], v[166:169], v[190:193], v[94:97]
	v_mfma_f32_16x16x32_bf16 v[90:93], v[174:177], v[190:193], v[90:93]
	v_mfma_f32_16x16x32_bf16 v[78:81], v[166:169], v[200:203], v[78:81]
	v_mfma_f32_16x16x32_bf16 v[74:77], v[174:177], v[200:203], v[74:77]
	v_mfma_f32_16x16x32_bf16 v[70:73], v[166:169], v[208:211], v[70:73]
	v_mfma_f32_16x16x32_bf16 v[66:69], v[174:177], v[208:211], v[66:69]
	v_mfma_f32_16x16x32_bf16 v[110:113], v[170:173], v[186:189], v[110:113]
	v_mfma_f32_16x16x32_bf16 v[106:109], v[178:181], v[186:189], v[106:109]
	v_mfma_f32_16x16x32_bf16 v[94:97], v[170:173], v[194:197], v[94:97]
	v_mfma_f32_16x16x32_bf16 v[90:93], v[178:181], v[194:197], v[90:93]
	v_mfma_f32_16x16x32_bf16 v[78:81], v[170:173], v[204:207], v[78:81]
	v_mfma_f32_16x16x32_bf16 v[74:77], v[178:181], v[204:207], v[74:77]
	v_mfma_f32_16x16x32_bf16 v[70:73], v[170:173], v[212:215], v[70:73]
	v_mfma_f32_16x16x32_bf16 v[66:69], v[178:181], v[212:215], v[66:69]
	s_setprio 0
	s_barrier
	s_add_i32 s16, s34, s20
	s_mov_b32 m0, s16
	ds_read_b128 v[182:185], v164 offset:49152
	ds_read_b128 v[186:189], v164 offset:50176
	ds_read_b128 v[190:193], v164 offset:51200
	ds_read_b128 v[194:197], v164 offset:52224
	ds_read_b128 v[200:203], v164 offset:53248
	ds_read_b128 v[204:207], v164 offset:54272
	ds_read_b128 v[208:211], v164 offset:55296
	ds_read_b128 v[212:215], v164 offset:56320
	global_load_lds_dwordx4 v0, s[98:99]
	s_add_i32 m0, s16, 0x2000
	s_add_u32 s14, s14, 0x80080
	s_addc_u32 s15, s15, 0
	s_add_i32 s16, s35, s20
	global_load_lds_dwordx4 v134, s[98:99]
	s_mov_b32 m0, s16
	s_nop 0
	global_load_lds_dwordx4 v0, s[14:15]
	s_add_i32 m0, s16, 0x2000
	s_nop 0
	global_load_lds_dwordx4 v134, s[14:15]
	s_mov_b32 m0, s26
	s_nop 0
	global_load_lds_dwordx4 v130, s[100:101]
	s_mov_b32 m0, s27
	s_nop 0
	global_load_lds_dwordx4 v132, s[100:101]
	s_waitcnt vmcnt(8)
	s_waitcnt lgkmcnt(0)
	s_barrier
	s_setprio 1
	s_add_i32 s42, s42, 2
	s_add_u32 s10, s10, 0x100
	s_addc_u32 s11, s11, 0
	s_add_u32 s18, s18, 0x100
	s_addc_u32 s33, s33, 0
	s_cmp_gt_u32 s42, 29
	v_mfma_f32_16x16x32_bf16 v[62:65], v[144:147], v[182:185], v[62:65]
	v_mfma_f32_16x16x32_bf16 v[58:61], v[152:155], v[182:185], v[58:61]
	v_mfma_f32_16x16x32_bf16 v[54:57], v[144:147], v[190:193], v[54:57]
	v_mfma_f32_16x16x32_bf16 v[50:53], v[152:155], v[190:193], v[50:53]
	v_mfma_f32_16x16x32_bf16 v[38:41], v[144:147], v[200:203], v[38:41]
	v_mfma_f32_16x16x32_bf16 v[34:37], v[152:155], v[200:203], v[34:37]
	v_mfma_f32_16x16x32_bf16 v[22:25], v[144:147], v[208:211], v[22:25]
	v_mfma_f32_16x16x32_bf16 v[18:21], v[152:155], v[208:211], v[18:21]
	v_mfma_f32_16x16x32_bf16 v[62:65], v[148:151], v[186:189], v[62:65]
	v_mfma_f32_16x16x32_bf16 v[58:61], v[156:159], v[186:189], v[58:61]
	v_mfma_f32_16x16x32_bf16 v[54:57], v[148:151], v[194:197], v[54:57]
	v_mfma_f32_16x16x32_bf16 v[50:53], v[156:159], v[194:197], v[50:53]
	v_mfma_f32_16x16x32_bf16 v[38:41], v[148:151], v[204:207], v[38:41]
	v_mfma_f32_16x16x32_bf16 v[34:37], v[156:159], v[204:207], v[34:37]
	v_mfma_f32_16x16x32_bf16 v[22:25], v[148:151], v[212:215], v[22:25]
	v_mfma_f32_16x16x32_bf16 v[18:21], v[156:159], v[212:215], v[18:21]
	s_setprio 0
	s_setprio 1
	v_mfma_f32_16x16x32_bf16 v[46:49], v[166:169], v[182:185], v[46:49]
	v_mfma_f32_16x16x32_bf16 v[42:45], v[174:177], v[182:185], v[42:45]
	v_mfma_f32_16x16x32_bf16 v[30:33], v[166:169], v[190:193], v[30:33]
	v_mfma_f32_16x16x32_bf16 v[26:29], v[174:177], v[190:193], v[26:29]
	v_mfma_f32_16x16x32_bf16 v[14:17], v[166:169], v[200:203], v[14:17]
	v_mfma_f32_16x16x32_bf16 v[10:13], v[174:177], v[200:203], v[10:13]
	v_mfma_f32_16x16x32_bf16 v[6:9], v[166:169], v[208:211], v[6:9]
	v_mfma_f32_16x16x32_bf16 v[2:5], v[174:177], v[208:211], v[2:5]
	v_mfma_f32_16x16x32_bf16 v[46:49], v[170:173], v[186:189], v[46:49]
	v_mfma_f32_16x16x32_bf16 v[42:45], v[178:181], v[186:189], v[42:45]
	v_mfma_f32_16x16x32_bf16 v[30:33], v[170:173], v[194:197], v[30:33]
	v_mfma_f32_16x16x32_bf16 v[26:29], v[178:181], v[194:197], v[26:29]
	v_mfma_f32_16x16x32_bf16 v[14:17], v[170:173], v[204:207], v[14:17]
	v_mfma_f32_16x16x32_bf16 v[10:13], v[178:181], v[204:207], v[10:13]
	v_mfma_f32_16x16x32_bf16 v[6:9], v[170:173], v[212:215], v[6:9]
	v_mfma_f32_16x16x32_bf16 v[2:5], v[178:181], v[212:215], v[2:5]
	s_setprio 0
	s_barrier
	s_cbranch_scc0 .LBB0_290
	s_and_b64 vcc, exec, s[2:3]
	s_cbranch_vccz .LBB0_293
	s_barrier

; #define PG8_STAGE(bufoff, gbase, voff) do { _Pragma("unroll") for (int _i = 0; _i < 2; ++_i) \
;         __builtin_amdgcn_global_load_lds((const unsigned*)((const char*)(gbase) + (voff)[_i]), (LAS unsigned*)(lds + (bufoff) + ldsw + _i * 8192), 16, 0, 0); } while (0)
; #define PG8_LDA(dst, b, h) do { _Pragma("unroll") for (int m = 0; m < 4; ++m) _Pragma("unroll") for (int k = 0; k < 2; ++k) dst[m][k] = *(const LAS bf16x8*)(lds + PG8_SA(b, h) + aoff + m * 2048 + k * 1024); } while (0)
; #define PG8_LDB(dst, b, h) do { _Pragma("unroll") for (int n = 0; n < 2; ++n) _Pragma("unroll") for (int k = 0; k < 2; ++k) dst[n][k] = *(const LAS bf16x8*)(lds + PG8_SB(b, h) + boff + n * 2048 + k * 1024); } while (0)
; #define PG8_MMA(ai, bj, At, Bt) do { __builtin_amdgcn_s_setprio(1); _Pragma("unroll") for (int m = 0; m < 4; ++m) _Pragma("unroll") for (int n = 0; n < 2; ++n) _Pragma("unroll") for (int k = 0; k < 2; ++k) \
;         acc[ai][bj][m][n] = __builtin_amdgcn_mfma_f32_16x16x32_bf16(Bt[n][k], At[m][k], acc[ai][bj][m][n], 0, 0, 0); __builtin_amdgcn_s_setprio(0); } while (0)
; #define PG8_WAIT_V(n) asm volatile("s_waitcnt vmcnt(" #n ")" ::: "memory")
; #define PG8_WAIT_L(n) asm volatile("s_waitcnt lgkmcnt(" #n ")" ::: "memory")
; #define PG8_BAR __builtin_amdgcn_s_barrier()
; #define PG8_SCHED __builtin_amdgcn_sched_barrier(0)
; template <class Epi, class Sched>
; __device__ __forceinline__ void gemm_phase(LAS unsigned char* lds, const int lda, const int ldb, const int K, const Sched& S, const Epi& E, int tid) {
;     ...
;         for (int t = 0; t < nt; t += 2) {
;             const bool last = (t == nt - 2);
;             const char* a1 = cA + (size_t)(t + 1) * kstep;
;             const char* a2 = last ? nA : cA + (size_t)(t + 2) * kstep; const char* b2 = last ? nB : cB + (size_t)(t + 2) * kstep;
;             const char* a3 = a2 + kstep; const char* b3 = b2 + kstep;
;             PG8_LDB(B0, 0, 0); PG8_LDB(B1, 0, 1); PG8_SCHED; PG8_LDA(At, 0, 0); PG8_STAGE(PG8_SA(1, 1), a1 + hA, voffA);
;             PG8_WAIT_V(8); PG8_WAIT_L(0); PG8_BAR; PG8_MMA(0, 0, At, B0); PG8_MMA(0, 1, At, B1); PG8_BAR; PG8_SCHED;
;             PG8_LDA(At, 0, 1); PG8_STAGE(PG8_SB(0, 0), b2, voffB); PG8_STAGE(PG8_SB(0, 1), b2 + hB, voffB); PG8_STAGE(PG8_SA(0, 0), a2, voffA);
;             PG8_WAIT_V(8); PG8_WAIT_L(0); PG8_BAR; PG8_MMA(1, 0, At, B0); PG8_MMA(1, 1, At, B1); PG8_BAR; PG8_SCHED;
.LBB0_448:
	s_add_u32 s10, s8, 0x100
	s_addc_u32 s11, s9, 0
	s_add_i32 s34, 0, 0x10000
	s_cmp_eq_u32 s44, 2
	s_cselect_b32 s17, s5, s11
	s_cselect_b32 s16, s4, s10
	s_cselect_b32 s15, s7, s43
	s_cselect_b32 s14, s6, s42
	s_add_i32 s35, 0, 0x14000
	v_add_u32_e32 v152, s34, v157
	v_add_u32_e32 v172, s35, v157
	ds_read_b128 v[130:133], v152
	ds_read_b128 v[134:137], v152 offset:1024
	ds_read_b128 v[148:151], v152 offset:2048
	ds_read_b128 v[152:155], v152 offset:3072
	ds_read_b128 v[160:163], v172
	ds_read_b128 v[164:167], v172 offset:1024
	ds_read_b128 v[168:171], v172 offset:2048
	ds_read_b128 v[172:175], v172 offset:3072
	s_add_i32 m0, s19, 0xc000
	ds_read_b128 v[176:179], v159
	ds_read_b128 v[180:183], v159 offset:1024
	ds_read_b128 v[184:187], v159 offset:2048
	ds_read_b128 v[188:191], v159 offset:3072
	ds_read_b128 v[192:195], v159 offset:4096
	ds_read_b128 v[200:203], v159 offset:5120
	ds_read_b128 v[204:207], v159 offset:6144
	ds_read_b128 v[208:211], v159 offset:7168
	global_load_lds_dwordx4 v144, s[8:9]
	s_add_i32 m0, s19, 0xe000
	s_nop 0
	global_load_lds_dwordx4 v146, s[8:9]
	s_waitcnt vmcnt(8)
	s_waitcnt lgkmcnt(0)
	s_barrier
	s_setprio 1
	v_mfma_f32_16x16x32_bf16 v[126:129], v[130:133], v[176:179], v[126:129]
	v_mfma_f32_16x16x32_bf16 v[122:125], v[148:151], v[176:179], v[122:125]
	v_mfma_f32_16x16x32_bf16 v[118:121], v[130:133], v[184:187], v[118:121]
	v_mfma_f32_16x16x32_bf16 v[114:117], v[148:151], v[184:187], v[114:117]
	v_mfma_f32_16x16x32_bf16 v[110:113], v[130:133], v[192:195], v[110:113]
	v_mfma_f32_16x16x32_bf16 v[106:109], v[148:151], v[192:195], v[106:109]
	v_mfma_f32_16x16x32_bf16 v[102:105], v[130:133], v[204:207], v[102:105]
	v_mfma_f32_16x16x32_bf16 v[98:101], v[148:151], v[204:207], v[98:101]
	v_mfma_f32_16x16x32_bf16 v[126:129], v[134:137], v[180:183], v[126:129]
	v_mfma_f32_16x16x32_bf16 v[122:125], v[152:155], v[180:183], v[122:125]
	v_mfma_f32_16x16x32_bf16 v[118:121], v[134:137], v[188:191], v[118:121]
	v_mfma_f32_16x16x32_bf16 v[114:117], v[152:155], v[188:191], v[114:117]
	v_mfma_f32_16x16x32_bf16 v[110:113], v[134:137], v[200:203], v[110:113]
	v_mfma_f32_16x16x32_bf16 v[106:109], v[152:155], v[200:203], v[106:109]
	v_mfma_f32_16x16x32_bf16 v[102:105], v[134:137], v[208:211], v[102:105]
	v_mfma_f32_16x16x32_bf16 v[98:101], v[152:155], v[208:211], v[98:101]
	s_setprio 0
	s_setprio 1
	v_mfma_f32_16x16x32_bf16 v[74:77], v[160:163], v[176:179], v[74:77]
	v_mfma_f32_16x16x32_bf16 v[66:69], v[168:171], v[176:179], v[66:69]
	v_mfma_f32_16x16x32_bf16 v[54:57], v[160:163], v[184:187], v[54:57]
	v_mfma_f32_16x16x32_bf16 v[50:53], v[168:171], v[184:187], v[50:53]
	v_mfma_f32_16x16x32_bf16 v[46:49], v[160:163], v[192:195], v[46:49]
	v_mfma_f32_16x16x32_bf16 v[42:45], v[168:171], v[192:195], v[42:45]
	v_mfma_f32_16x16x32_bf16 v[38:41], v[160:163], v[204:207], v[38:41]
	v_mfma_f32_16x16x32_bf16 v[34:37], v[168:171], v[204:207], v[34:37]
	v_mfma_f32_16x16x32_bf16 v[74:77], v[164:167], v[180:183], v[74:77]
	v_mfma_f32_16x16x32_bf16 v[66:69], v[172:175], v[180:183], v[66:69]
	v_mfma_f32_16x16x32_bf16 v[54:57], v[164:167], v[188:191], v[54:57]
	v_mfma_f32_16x16x32_bf16 v[50:53], v[172:175], v[188:191], v[50:53]
	v_mfma_f32_16x16x32_bf16 v[46:49], v[164:167], v[200:203], v[46:49]
	v_mfma_f32_16x16x32_bf16 v[42:45], v[172:175], v[200:203], v[42:45]
	v_mfma_f32_16x16x32_bf16 v[38:41], v[164:167], v[208:211], v[38:41]
	v_mfma_f32_16x16x32_bf16 v[34:37], v[172:175], v[208:211], v[34:37]
	s_setprio 0
	s_barrier
	s_add_u32 s98, s14, s30
	s_addc_u32 s99, s15, s31
	s_add_u32 s100, s16, s30
	s_addc_u32 s101, s17, s31
	s_add_i32 s8, s34, s18
	s_mov_b32 m0, s8
	ds_read_b128 v[176:179], v159 offset:16384
	ds_read_b128 v[180:183], v159 offset:17408
	ds_read_b128 v[184:187], v159 offset:18432
	ds_read_b128 v[188:191], v159 offset:19456
	ds_read_b128 v[192:195], v159 offset:20480
	ds_read_b128 v[200:203], v159 offset:21504
	ds_read_b128 v[204:207], v159 offset:22528
	ds_read_b128 v[208:211], v159 offset:23552
	global_load_lds_dwordx4 v0, s[14:15]
	s_add_i32 m0, s8, 0x2000
	s_add_u32 s8, s14, 0x18000
	s_addc_u32 s9, s15, 0
	s_add_i32 s34, s35, s18
	global_load_lds_dwordx4 v142, s[14:15]
	s_mov_b32 m0, s34
	s_nop 0
	global_load_lds_dwordx4 v0, s[8:9]
	s_add_i32 m0, s34, 0x2000
	s_nop 0
	global_load_lds_dwordx4 v142, s[8:9]
	s_mov_b32 m0, s19
	s_nop 0
	global_load_lds_dwordx4 v138, s[16:17]
	s_mov_b32 m0, s20
	s_nop 0
	global_load_lds_dwordx4 v140, s[16:17]
	s_waitcnt vmcnt(8)
	s_waitcnt lgkmcnt(0)
	s_barrier
	s_setprio 1
	v_mfma_f32_16x16x32_bf16 v[94:97], v[130:133], v[176:179], v[94:97]
	v_mfma_f32_16x16x32_bf16 v[90:93], v[148:151], v[176:179], v[90:93]
	v_mfma_f32_16x16x32_bf16 v[86:89], v[130:133], v[184:187], v[86:89]
	v_mfma_f32_16x16x32_bf16 v[82:85], v[148:151], v[184:187], v[82:85]
	v_mfma_f32_16x16x32_bf16 v[78:81], v[130:133], v[192:195], v[78:81]
	v_mfma_f32_16x16x32_bf16 v[70:73], v[148:151], v[192:195], v[70:73]
	v_mfma_f32_16x16x32_bf16 v[62:65], v[130:133], v[204:207], v[62:65]
	v_mfma_f32_16x16x32_bf16 v[58:61], v[148:151], v[204:207], v[58:61]
	v_mfma_f32_16x16x32_bf16 v[94:97], v[134:137], v[180:183], v[94:97]
	v_mfma_f32_16x16x32_bf16 v[90:93], v[152:155], v[180:183], v[90:93]
	v_mfma_f32_16x16x32_bf16 v[86:89], v[134:137], v[188:191], v[86:89]
	v_mfma_f32_16x16x32_bf16 v[82:85], v[152:155], v[188:191], v[82:85]
	v_mfma_f32_16x16x32_bf16 v[78:81], v[134:137], v[200:203], v[78:81]
	v_mfma_f32_16x16x32_bf16 v[70:73], v[152:155], v[200:203], v[70:73]
	v_mfma_f32_16x16x32_bf16 v[62:65], v[134:137], v[208:211], v[62:65]
	v_mfma_f32_16x16x32_bf16 v[58:61], v[152:155], v[208:211], v[58:61]
	s_setprio 0
	s_setprio 1
	v_mfma_f32_16x16x32_bf16 v[30:33], v[160:163], v[176:179], v[30:33]
	v_mfma_f32_16x16x32_bf16 v[26:29], v[168:171], v[176:179], v[26:29]
	v_mfma_f32_16x16x32_bf16 v[22:25], v[160:163], v[184:187], v[22:25]
	v_mfma_f32_16x16x32_bf16 v[18:21], v[168:171], v[184:187], v[18:21]
	v_mfma_f32_16x16x32_bf16 v[14:17], v[160:163], v[192:195], v[14:17]
	v_mfma_f32_16x16x32_bf16 v[10:13], v[168:171], v[192:195], v[10:13]
	v_mfma_f32_16x16x32_bf16 v[6:9], v[160:163], v[204:207], v[6:9]
	v_mfma_f32_16x16x32_bf16 v[2:5], v[168:171], v[204:207], v[2:5]
	v_mfma_f32_16x16x32_bf16 v[30:33], v[164:167], v[180:183], v[30:33]
	v_mfma_f32_16x16x32_bf16 v[26:29], v[172:175], v[180:183], v[26:29]
	v_mfma_f32_16x16x32_bf16 v[22:25], v[164:167], v[188:191], v[22:25]
	v_mfma_f32_16x16x32_bf16 v[18:21], v[172:175], v[188:191], v[18:21]
	v_mfma_f32_16x16x32_bf16 v[14:17], v[164:167], v[200:203], v[14:17]
	v_mfma_f32_16x16x32_bf16 v[10:13], v[172:175], v[200:203], v[10:13]
	v_mfma_f32_16x16x32_bf16 v[6:9], v[164:167], v[208:211], v[6:9]
	v_mfma_f32_16x16x32_bf16 v[2:5], v[172:175], v[208:211], v[2:5]
	s_setprio 0
	s_barrier
; #define PG8_STAGE(bufoff, gbase, voff) do { _Pragma("unroll") for (int _i = 0; _i < 2; ++_i) \
;         __builtin_amdgcn_global_load_lds((const unsigned*)((const char*)(gbase) + (voff)[_i]), (LAS unsigned*)(lds + (bufoff) + ldsw + _i * 8192), 16, 0, 0); } while (0)
; #define PG8_LDA(dst, b, h) do { _Pragma("unroll") for (int m = 0; m < 4; ++m) _Pragma("unroll") for (int k = 0; k < 2; ++k) dst[m][k] = *(const LAS bf16x8*)(lds + PG8_SA(b, h) + aoff + m * 2048 + k * 1024); } while (0)
; #define PG8_LDB(dst, b, h) do { _Pragma("unroll") for (int n = 0; n < 2; ++n) _Pragma("unroll") for (int k = 0; k < 2; ++k) dst[n][k] = *(const LAS bf16x8*)(lds + PG8_SB(b, h) + boff + n * 2048 + k * 1024); } while (0)
; #define PG8_MMA(ai, bj, At, Bt) do { __builtin_amdgcn_s_setprio(1); _Pragma("unroll") for (int m = 0; m < 4; ++m) _Pragma("unroll") for (int n = 0; n < 2; ++n) _Pragma("unroll") for (int k = 0; k < 2; ++k) \
;         acc[ai][bj][m][n] = __builtin_amdgcn_mfma_f32_16x16x32_bf16(Bt[n][k], At[m][k], acc[ai][bj][m][n], 0, 0, 0); __builtin_amdgcn_s_setprio(0); } while (0)
; #define PG8_WAIT_V(n) asm volatile("s_waitcnt vmcnt(" #n ")" ::: "memory")
; #define PG8_WAIT_L(n) asm volatile("s_waitcnt lgkmcnt(" #n ")" ::: "memory")
; #define PG8_BAR __builtin_amdgcn_s_barrier()
; #define PG8_SCHED __builtin_amdgcn_sched_barrier(0)
; template <class Epi, class Sched>
; __device__ __forceinline__ void gemm_phase(LAS unsigned char* lds, const int lda, const int ldb, const int K, const Sched& S, const Epi& E, int tid) {
;     ...
;             PG8_LDB(B0, 1, 0); PG8_LDB(B1, 1, 1); PG8_SCHED; PG8_LDA(At, 1, 0); PG8_STAGE(PG8_SA(0, 1), a2 + hA, voffA);
;             PG8_WAIT_V(8); PG8_WAIT_L(0); PG8_BAR; PG8_MMA(0, 0, At, B0); PG8_MMA(0, 1, At, B1); PG8_BAR; PG8_SCHED;
;             PG8_LDA(At, 1, 1); PG8_STAGE(PG8_SB(1, 0), b3, voffB); PG8_STAGE(PG8_SB(1, 1), b3 + hB, voffB); PG8_STAGE(PG8_SA(1, 0), a3, voffA);
;             PG8_WAIT_V(8); PG8_WAIT_L(0); PG8_BAR; PG8_MMA(1, 0, At, B0); PG8_MMA(1, 1, At, B1); PG8_BAR; PG8_SCHED;
;         }
;         if (wr == 0) PG8_BAR;
	s_add_i32 s34, 0, 0x18000
	s_add_i32 s35, 0, 0x1c000
	v_add_u32_e32 v152, s34, v157
	v_add_u32_e32 v172, s35, v157
	ds_read_b128 v[130:133], v152
	ds_read_b128 v[134:137], v152 offset:1024
	ds_read_b128 v[148:151], v152 offset:2048
	ds_read_b128 v[152:155], v152 offset:3072
	ds_read_b128 v[160:163], v172
	ds_read_b128 v[164:167], v172 offset:1024
	ds_read_b128 v[168:171], v172 offset:2048
	ds_read_b128 v[172:175], v172 offset:3072
	s_add_u32 s8, s16, 0x60000
	s_addc_u32 s9, s17, 0
	s_mov_b32 m0, s21
	ds_read_b128 v[176:179], v159 offset:32768
	ds_read_b128 v[180:183], v159 offset:33792
	ds_read_b128 v[184:187], v159 offset:34816
	ds_read_b128 v[188:191], v159 offset:35840
	ds_read_b128 v[192:195], v159 offset:36864
	ds_read_b128 v[200:203], v159 offset:37888
	ds_read_b128 v[204:207], v159 offset:38912
	ds_read_b128 v[208:211], v159 offset:39936
	global_load_lds_dwordx4 v138, s[8:9]
	s_mov_b32 m0, s22
	s_nop 0
	global_load_lds_dwordx4 v140, s[8:9]
	s_waitcnt vmcnt(8)
	s_waitcnt lgkmcnt(0)
	s_barrier
	s_setprio 1
	v_mfma_f32_16x16x32_bf16 v[126:129], v[130:133], v[176:179], v[126:129]
	v_mfma_f32_16x16x32_bf16 v[122:125], v[148:151], v[176:179], v[122:125]
	v_mfma_f32_16x16x32_bf16 v[118:121], v[130:133], v[184:187], v[118:121]
	v_mfma_f32_16x16x32_bf16 v[114:117], v[148:151], v[184:187], v[114:117]
	v_mfma_f32_16x16x32_bf16 v[110:113], v[130:133], v[192:195], v[110:113]
	v_mfma_f32_16x16x32_bf16 v[106:109], v[148:151], v[192:195], v[106:109]
	v_mfma_f32_16x16x32_bf16 v[102:105], v[130:133], v[204:207], v[102:105]
	v_mfma_f32_16x16x32_bf16 v[98:101], v[148:151], v[204:207], v[98:101]
	v_mfma_f32_16x16x32_bf16 v[126:129], v[134:137], v[180:183], v[126:129]
	v_mfma_f32_16x16x32_bf16 v[122:125], v[152:155], v[180:183], v[122:125]
	v_mfma_f32_16x16x32_bf16 v[118:121], v[134:137], v[188:191], v[118:121]
	v_mfma_f32_16x16x32_bf16 v[114:117], v[152:155], v[188:191], v[114:117]
	v_mfma_f32_16x16x32_bf16 v[110:113], v[134:137], v[200:203], v[110:113]
	v_mfma_f32_16x16x32_bf16 v[106:109], v[152:155], v[200:203], v[106:109]
	v_mfma_f32_16x16x32_bf16 v[102:105], v[134:137], v[208:211], v[102:105]
	v_mfma_f32_16x16x32_bf16 v[98:101], v[152:155], v[208:211], v[98:101]
	s_setprio 0
	s_setprio 1
	v_mfma_f32_16x16x32_bf16 v[74:77], v[160:163], v[176:179], v[74:77]
	v_mfma_f32_16x16x32_bf16 v[66:69], v[168:171], v[176:179], v[66:69]
	v_mfma_f32_16x16x32_bf16 v[54:57], v[160:163], v[184:187], v[54:57]
	v_mfma_f32_16x16x32_bf16 v[50:53], v[168:171], v[184:187], v[50:53]
	v_mfma_f32_16x16x32_bf16 v[46:49], v[160:163], v[192:195], v[46:49]
	v_mfma_f32_16x16x32_bf16 v[42:45], v[168:171], v[192:195], v[42:45]
	v_mfma_f32_16x16x32_bf16 v[38:41], v[160:163], v[204:207], v[38:41]
	v_mfma_f32_16x16x32_bf16 v[34:37], v[168:171], v[204:207], v[34:37]
	v_mfma_f32_16x16x32_bf16 v[74:77], v[164:167], v[180:183], v[74:77]
	v_mfma_f32_16x16x32_bf16 v[66:69], v[172:175], v[180:183], v[66:69]
	v_mfma_f32_16x16x32_bf16 v[54:57], v[164:167], v[188:191], v[54:57]
	v_mfma_f32_16x16x32_bf16 v[50:53], v[172:175], v[188:191], v[50:53]
	v_mfma_f32_16x16x32_bf16 v[46:49], v[164:167], v[200:203], v[46:49]
	v_mfma_f32_16x16x32_bf16 v[42:45], v[172:175], v[200:203], v[42:45]
	v_mfma_f32_16x16x32_bf16 v[38:41], v[164:167], v[208:211], v[38:41]
	v_mfma_f32_16x16x32_bf16 v[34:37], v[172:175], v[208:211], v[34:37]
	s_setprio 0
	s_barrier
	s_add_i32 s8, s34, s18
	s_mov_b32 m0, s8
	ds_read_b128 v[176:179], v159 offset:49152
	ds_read_b128 v[180:183], v159 offset:50176
	ds_read_b128 v[184:187], v159 offset:51200
	ds_read_b128 v[188:191], v159 offset:52224
	ds_read_b128 v[192:195], v159 offset:53248
	ds_read_b128 v[200:203], v159 offset:54272
	ds_read_b128 v[204:207], v159 offset:55296
	ds_read_b128 v[208:211], v159 offset:56320
	global_load_lds_dwordx4 v0, s[98:99]
	s_add_i32 m0, s8, 0x2000
	s_add_u32 s8, s14, 0x18080
	s_addc_u32 s9, s15, 0
	s_add_i32 s14, s35, s18
	global_load_lds_dwordx4 v142, s[98:99]
	s_mov_b32 m0, s14
	s_nop 0
	global_load_lds_dwordx4 v0, s[8:9]
	s_add_i32 m0, s14, 0x2000
	s_nop 0
	global_load_lds_dwordx4 v142, s[8:9]
	s_mov_b32 m0, s23
	s_nop 0
	global_load_lds_dwordx4 v138, s[100:101]
	s_mov_b32 m0, s25
	s_nop 0
	global_load_lds_dwordx4 v140, s[100:101]
	s_waitcnt vmcnt(8)
	s_waitcnt lgkmcnt(0)
	s_barrier
	s_setprio 1
	s_add_i32 s44, s44, 2
	s_add_u32 s42, s42, 0x100
	s_addc_u32 s43, s43, 0
	s_cmp_gt_u32 s44, 3
	s_mov_b64 s[8:9], s[10:11]
	v_mfma_f32_16x16x32_bf16 v[94:97], v[130:133], v[176:179], v[94:97]
	v_mfma_f32_16x16x32_bf16 v[90:93], v[148:151], v[176:179], v[90:93]
	v_mfma_f32_16x16x32_bf16 v[86:89], v[130:133], v[184:187], v[86:89]
	v_mfma_f32_16x16x32_bf16 v[82:85], v[148:151], v[184:187], v[82:85]
	v_mfma_f32_16x16x32_bf16 v[78:81], v[130:133], v[192:195], v[78:81]
	v_mfma_f32_16x16x32_bf16 v[70:73], v[148:151], v[192:195], v[70:73]
	v_mfma_f32_16x16x32_bf16 v[62:65], v[130:133], v[204:207], v[62:65]
	v_mfma_f32_16x16x32_bf16 v[58:61], v[148:151], v[204:207], v[58:61]
	v_mfma_f32_16x16x32_bf16 v[94:97], v[134:137], v[180:183], v[94:97]
	v_mfma_f32_16x16x32_bf16 v[90:93], v[152:155], v[180:183], v[90:93]
	v_mfma_f32_16x16x32_bf16 v[86:89], v[134:137], v[188:191], v[86:89]
	v_mfma_f32_16x16x32_bf16 v[82:85], v[152:155], v[188:191], v[82:85]
	v_mfma_f32_16x16x32_bf16 v[78:81], v[134:137], v[200:203], v[78:81]
	v_mfma_f32_16x16x32_bf16 v[70:73], v[152:155], v[200:203], v[70:73]
	v_mfma_f32_16x16x32_bf16 v[62:65], v[134:137], v[208:211], v[62:65]
	v_mfma_f32_16x16x32_bf16 v[58:61], v[152:155], v[208:211], v[58:61]
	s_setprio 0
	s_setprio 1
	v_mfma_f32_16x16x32_bf16 v[30:33], v[160:163], v[176:179], v[30:33]
	v_mfma_f32_16x16x32_bf16 v[26:29], v[168:171], v[176:179], v[26:29]
	v_mfma_f32_16x16x32_bf16 v[22:25], v[160:163], v[184:187], v[22:25]
	v_mfma_f32_16x16x32_bf16 v[18:21], v[168:171], v[184:187], v[18:21]
	v_mfma_f32_16x16x32_bf16 v[14:17], v[160:163], v[192:195], v[14:17]
	v_mfma_f32_16x16x32_bf16 v[10:13], v[168:171], v[192:195], v[10:13]
	v_mfma_f32_16x16x32_bf16 v[6:9], v[160:163], v[204:207], v[6:9]
	v_mfma_f32_16x16x32_bf16 v[2:5], v[168:171], v[204:207], v[2:5]
	v_mfma_f32_16x16x32_bf16 v[30:33], v[164:167], v[180:183], v[30:33]
	v_mfma_f32_16x16x32_bf16 v[26:29], v[172:175], v[180:183], v[26:29]
	v_mfma_f32_16x16x32_bf16 v[22:25], v[164:167], v[188:191], v[22:25]
	v_mfma_f32_16x16x32_bf16 v[18:21], v[172:175], v[188:191], v[18:21]
	v_mfma_f32_16x16x32_bf16 v[14:17], v[164:167], v[200:203], v[14:17]
	v_mfma_f32_16x16x32_bf16 v[10:13], v[172:175], v[200:203], v[10:13]
	v_mfma_f32_16x16x32_bf16 v[6:9], v[164:167], v[208:211], v[6:9]
	v_mfma_f32_16x16x32_bf16 v[2:5], v[172:175], v[208:211], v[2:5]
	s_setprio 0
	s_barrier
	s_cbranch_scc0 .LBB0_448
	s_and_b64 vcc, exec, s[2:3]
	s_cbranch_vccz .LBB0_451
	s_barrier

; #define PG8_STAGE(bufoff, gbase, voff) do { _Pragma("unroll") for (int _i = 0; _i < 2; ++_i) \
;         __builtin_amdgcn_global_load_lds((const unsigned*)((const char*)(gbase) + (voff)[_i]), (LAS unsigned*)(lds + (bufoff) + ldsw + _i * 8192), 16, 0, 0); } while (0)
; #define PG8_LDA(dst, b, h) do { _Pragma("unroll") for (int m = 0; m < 4; ++m) _Pragma("unroll") for (int k = 0; k < 2; ++k) dst[m][k] = *(const LAS bf16x8*)(lds + PG8_SA(b, h) + aoff + m * 2048 + k * 1024); } while (0)
; #define PG8_LDB(dst, b, h) do { _Pragma("unroll") for (int n = 0; n < 2; ++n) _Pragma("unroll") for (int k = 0; k < 2; ++k) dst[n][k] = *(const LAS bf16x8*)(lds + PG8_SB(b, h) + boff + n * 2048 + k * 1024); } while (0)
; #define PG8_MMA(ai, bj, At, Bt) do { __builtin_amdgcn_s_setprio(1); _Pragma("unroll") for (int m = 0; m < 4; ++m) _Pragma("unroll") for (int n = 0; n < 2; ++n) _Pragma("unroll") for (int k = 0; k < 2; ++k) \
;         acc[ai][bj][m][n] = __builtin_amdgcn_mfma_f32_16x16x32_bf16(Bt[n][k], At[m][k], acc[ai][bj][m][n], 0, 0, 0); __builtin_amdgcn_s_setprio(0); } while (0)
; #define PG8_WAIT_V(n) asm volatile("s_waitcnt vmcnt(" #n ")" ::: "memory")
; #define PG8_WAIT_L(n) asm volatile("s_waitcnt lgkmcnt(" #n ")" ::: "memory")
; #define PG8_BAR __builtin_amdgcn_s_barrier()
; #define PG8_SCHED __builtin_amdgcn_sched_barrier(0)
; template <class Epi, class Sched>
; __device__ __forceinline__ void gemm_phase(LAS unsigned char* lds, const int lda, const int ldb, const int K, const Sched& S, const Epi& E, int tid) {
;     ...
;         for (int t = 0; t < nt; t += 2) {
;             const bool last = (t == nt - 2);
;             const char* a1 = cA + (size_t)(t + 1) * kstep;
;             const char* a2 = last ? nA : cA + (size_t)(t + 2) * kstep; const char* b2 = last ? nB : cB + (size_t)(t + 2) * kstep;
;             const char* a3 = a2 + kstep; const char* b3 = b2 + kstep;
;             PG8_LDB(B0, 0, 0); PG8_LDB(B1, 0, 1); PG8_SCHED; PG8_LDA(At, 0, 0); PG8_STAGE(PG8_SA(1, 1), a1 + hA, voffA);
;             PG8_WAIT_V(8); PG8_WAIT_L(0); PG8_BAR; PG8_MMA(0, 0, At, B0); PG8_MMA(0, 1, At, B1); PG8_BAR; PG8_SCHED;
;             PG8_LDA(At, 0, 1); PG8_STAGE(PG8_SB(0, 0), b2, voffB); PG8_STAGE(PG8_SB(0, 1), b2 + hB, voffB); PG8_STAGE(PG8_SA(0, 0), a2, voffA);
;             PG8_WAIT_V(8); PG8_WAIT_L(0); PG8_BAR; PG8_MMA(1, 0, At, B0); PG8_MMA(1, 1, At, B1); PG8_BAR; PG8_SCHED;
.LBB0_530:
	s_add_u32 s8, s6, 0xfff80080
	s_addc_u32 s9, s7, -1
	s_add_i32 s16, 0, 0x10000
	s_cmp_eq_u32 s15, 28
	s_cselect_b32 s11, s53, s9
	s_cselect_b32 s10, s52, s8
	v_add_u32_e32 v106, s16, v208
	s_cselect_b32 s9, s55, s14
	s_cselect_b32 s8, s54, s3
	s_add_i32 s22, 0, 0x14000
	ds_read_b128 v[102:105], v106
	ds_read_b128 v[128:131], v106 offset:1024
	ds_read_b128 v[132:135], v106 offset:2048
	ds_read_b128 v[154:157], v106 offset:3072
	v_add_u32_e32 v106, s22, v208
	ds_read_b128 v[158:161], v106
	ds_read_b128 v[162:165], v106 offset:1024
	ds_read_b128 v[166:169], v106 offset:2048
	ds_read_b128 v[170:173], v106 offset:3072
	s_add_i32 m0, s20, 0xc000
	ds_read_b128 v[174:177], v210
	ds_read_b128 v[178:181], v210 offset:1024
	ds_read_b128 v[182:185], v210 offset:2048
	ds_read_b128 v[186:189], v210 offset:3072
	ds_read_b128 v[190:193], v210 offset:4096
	ds_read_b128 v[194:197], v210 offset:5120
	ds_read_b128 v[200:203], v210 offset:6144
	ds_read_b128 v[204:207], v210 offset:7168
	global_load_lds_dwordx4 v150, s[6:7]
	s_add_i32 m0, s20, 0xe000
	s_nop 0
	global_load_lds_dwordx4 v152, s[6:7]
	s_waitcnt vmcnt(8)
	s_waitcnt lgkmcnt(0)
	s_barrier
	s_setprio 1
	v_mfma_f32_16x16x32_bf16 v[140:143], v[102:105], v[174:177], v[140:143]
	v_mfma_f32_16x16x32_bf16 v[94:97], v[132:135], v[174:177], v[94:97]
	v_mfma_f32_16x16x32_bf16 v[136:139], v[102:105], v[182:185], v[136:139]
	v_mfma_f32_16x16x32_bf16 v[90:93], v[132:135], v[182:185], v[90:93]
	v_mfma_f32_16x16x32_bf16 v[124:127], v[102:105], v[190:193], v[124:127]
	v_mfma_f32_16x16x32_bf16 v[86:89], v[132:135], v[190:193], v[86:89]
	v_mfma_f32_16x16x32_bf16 v[120:123], v[102:105], v[200:203], v[120:123]
	v_mfma_f32_16x16x32_bf16 v[82:85], v[132:135], v[200:203], v[82:85]
	v_mfma_f32_16x16x32_bf16 v[140:143], v[128:131], v[178:181], v[140:143]
	v_mfma_f32_16x16x32_bf16 v[94:97], v[154:157], v[178:181], v[94:97]
	v_mfma_f32_16x16x32_bf16 v[136:139], v[128:131], v[186:189], v[136:139]
	v_mfma_f32_16x16x32_bf16 v[90:93], v[154:157], v[186:189], v[90:93]
	v_mfma_f32_16x16x32_bf16 v[124:127], v[128:131], v[194:197], v[124:127]
	v_mfma_f32_16x16x32_bf16 v[86:89], v[154:157], v[194:197], v[86:89]
	v_mfma_f32_16x16x32_bf16 v[120:123], v[128:131], v[204:207], v[120:123]
	v_mfma_f32_16x16x32_bf16 v[82:85], v[154:157], v[204:207], v[82:85]
	s_setprio 0
	s_setprio 1
	v_mfma_f32_16x16x32_bf16 v[62:65], v[158:161], v[174:177], v[62:65]
	v_mfma_f32_16x16x32_bf16 v[34:37], v[166:169], v[174:177], v[34:37]
	v_mfma_f32_16x16x32_bf16 v[58:61], v[158:161], v[182:185], v[58:61]
	v_mfma_f32_16x16x32_bf16 v[26:29], v[166:169], v[182:185], v[26:29]
	v_mfma_f32_16x16x32_bf16 v[54:57], v[158:161], v[190:193], v[54:57]
	v_mfma_f32_16x16x32_bf16 v[22:25], v[166:169], v[190:193], v[22:25]
	v_mfma_f32_16x16x32_bf16 v[50:53], v[158:161], v[200:203], v[50:53]
	v_mfma_f32_16x16x32_bf16 v[18:21], v[166:169], v[200:203], v[18:21]
	v_mfma_f32_16x16x32_bf16 v[62:65], v[162:165], v[178:181], v[62:65]
	v_mfma_f32_16x16x32_bf16 v[34:37], v[170:173], v[178:181], v[34:37]
	v_mfma_f32_16x16x32_bf16 v[58:61], v[162:165], v[186:189], v[58:61]
	v_mfma_f32_16x16x32_bf16 v[26:29], v[170:173], v[186:189], v[26:29]
	v_mfma_f32_16x16x32_bf16 v[54:57], v[162:165], v[194:197], v[54:57]
	v_mfma_f32_16x16x32_bf16 v[22:25], v[170:173], v[194:197], v[22:25]
	v_mfma_f32_16x16x32_bf16 v[50:53], v[162:165], v[204:207], v[50:53]
	v_mfma_f32_16x16x32_bf16 v[18:21], v[170:173], v[204:207], v[18:21]
	s_setprio 0
	s_barrier
	s_add_u32 s98, s8, s30
	s_addc_u32 s99, s9, s31
	s_add_u32 s100, s10, s30
	s_addc_u32 s101, s11, s31
	s_add_i32 s16, s16, s5
	s_mov_b32 m0, s16
	ds_read_b128 v[174:177], v210 offset:16384
	ds_read_b128 v[178:181], v210 offset:17408
	ds_read_b128 v[182:185], v210 offset:18432
	ds_read_b128 v[186:189], v210 offset:19456
	ds_read_b128 v[190:193], v210 offset:20480
	ds_read_b128 v[194:197], v210 offset:21504
	ds_read_b128 v[200:203], v210 offset:22528
	ds_read_b128 v[204:207], v210 offset:23552
	global_load_lds_dwordx4 v0, s[8:9]
	s_add_i32 m0, s16, 0x2000
	s_add_u32 s16, s8, 0x80000
	s_addc_u32 s17, s9, 0
	s_add_i32 s22, s22, s5
	global_load_lds_dwordx4 v148, s[8:9]
	s_mov_b32 m0, s22
	s_nop 0
	global_load_lds_dwordx4 v0, s[16:17]
	s_add_i32 m0, s22, 0x2000
	s_nop 0
	global_load_lds_dwordx4 v148, s[16:17]
	s_mov_b32 m0, s20
	s_nop 0
	global_load_lds_dwordx4 v144, s[10:11]
	s_mov_b32 m0, s21
	s_nop 0
	global_load_lds_dwordx4 v146, s[10:11]
	s_waitcnt vmcnt(8)
	s_waitcnt lgkmcnt(0)
	s_barrier
	s_setprio 1
	v_mfma_f32_16x16x32_bf16 v[116:119], v[102:105], v[174:177], v[116:119]
	v_mfma_f32_16x16x32_bf16 v[78:81], v[132:135], v[174:177], v[78:81]
	v_mfma_f32_16x16x32_bf16 v[112:115], v[102:105], v[182:185], v[112:115]
	v_mfma_f32_16x16x32_bf16 v[74:77], v[132:135], v[182:185], v[74:77]
	v_mfma_f32_16x16x32_bf16 v[106:109], v[102:105], v[190:193], v[108:111]
	v_mfma_f32_16x16x32_bf16 v[70:73], v[132:135], v[190:193], v[70:73]
	v_mfma_f32_16x16x32_bf16 v[98:101], v[102:105], v[200:203], v[98:101]
	v_mfma_f32_16x16x32_bf16 v[66:69], v[132:135], v[200:203], v[66:69]
	v_mfma_f32_16x16x32_bf16 v[116:119], v[128:131], v[178:181], v[116:119]
	v_mfma_f32_16x16x32_bf16 v[78:81], v[154:157], v[178:181], v[78:81]
	v_mfma_f32_16x16x32_bf16 v[112:115], v[128:131], v[186:189], v[112:115]
	v_mfma_f32_16x16x32_bf16 v[74:77], v[154:157], v[186:189], v[74:77]
	v_mfma_f32_16x16x32_bf16 v[106:109], v[128:131], v[194:197], v[106:109]
	v_mfma_f32_16x16x32_bf16 v[70:73], v[154:157], v[194:197], v[70:73]
	v_mfma_f32_16x16x32_bf16 v[98:101], v[128:131], v[204:207], v[98:101]
	v_mfma_f32_16x16x32_bf16 v[66:69], v[154:157], v[204:207], v[66:69]
	s_setprio 0
	s_setprio 1
	v_mfma_f32_16x16x32_bf16 v[46:49], v[158:161], v[174:177], v[46:49]
	v_mfma_f32_16x16x32_bf16 v[14:17], v[166:169], v[174:177], v[14:17]
	v_mfma_f32_16x16x32_bf16 v[42:45], v[158:161], v[182:185], v[42:45]
	v_mfma_f32_16x16x32_bf16 v[10:13], v[166:169], v[182:185], v[10:13]
	v_mfma_f32_16x16x32_bf16 v[38:41], v[158:161], v[190:193], v[38:41]
	v_mfma_f32_16x16x32_bf16 v[6:9], v[166:169], v[190:193], v[6:9]
	v_mfma_f32_16x16x32_bf16 v[30:33], v[158:161], v[200:203], v[30:33]
	v_mfma_f32_16x16x32_bf16 v[2:5], v[166:169], v[200:203], v[2:5]
	v_mfma_f32_16x16x32_bf16 v[46:49], v[162:165], v[178:181], v[46:49]
	v_mfma_f32_16x16x32_bf16 v[14:17], v[170:173], v[178:181], v[14:17]
	v_mfma_f32_16x16x32_bf16 v[42:45], v[162:165], v[186:189], v[42:45]
	v_mfma_f32_16x16x32_bf16 v[10:13], v[170:173], v[186:189], v[10:13]
	v_mfma_f32_16x16x32_bf16 v[38:41], v[162:165], v[194:197], v[38:41]
	v_mfma_f32_16x16x32_bf16 v[6:9], v[170:173], v[194:197], v[6:9]
	v_mfma_f32_16x16x32_bf16 v[30:33], v[162:165], v[204:207], v[30:33]
	v_mfma_f32_16x16x32_bf16 v[2:5], v[170:173], v[204:207], v[2:5]
	s_setprio 0
	s_barrier
; #define PG8_STAGE(bufoff, gbase, voff) do { _Pragma("unroll") for (int _i = 0; _i < 2; ++_i) \
;         __builtin_amdgcn_global_load_lds((const unsigned*)((const char*)(gbase) + (voff)[_i]), (LAS unsigned*)(lds + (bufoff) + ldsw + _i * 8192), 16, 0, 0); } while (0)
; #define PG8_LDA(dst, b, h) do { _Pragma("unroll") for (int m = 0; m < 4; ++m) _Pragma("unroll") for (int k = 0; k < 2; ++k) dst[m][k] = *(const LAS bf16x8*)(lds + PG8_SA(b, h) + aoff + m * 2048 + k * 1024); } while (0)
; #define PG8_LDB(dst, b, h) do { _Pragma("unroll") for (int n = 0; n < 2; ++n) _Pragma("unroll") for (int k = 0; k < 2; ++k) dst[n][k] = *(const LAS bf16x8*)(lds + PG8_SB(b, h) + boff + n * 2048 + k * 1024); } while (0)
; #define PG8_MMA(ai, bj, At, Bt) do { __builtin_amdgcn_s_setprio(1); _Pragma("unroll") for (int m = 0; m < 4; ++m) _Pragma("unroll") for (int n = 0; n < 2; ++n) _Pragma("unroll") for (int k = 0; k < 2; ++k) \
;         acc[ai][bj][m][n] = __builtin_amdgcn_mfma_f32_16x16x32_bf16(Bt[n][k], At[m][k], acc[ai][bj][m][n], 0, 0, 0); __builtin_amdgcn_s_setprio(0); } while (0)
; #define PG8_WAIT_V(n) asm volatile("s_waitcnt vmcnt(" #n ")" ::: "memory")
; #define PG8_WAIT_L(n) asm volatile("s_waitcnt lgkmcnt(" #n ")" ::: "memory")
; #define PG8_BAR __builtin_amdgcn_s_barrier()
; #define PG8_SCHED __builtin_amdgcn_sched_barrier(0)
; template <class Epi, class Sched>
; __device__ __forceinline__ void gemm_phase(LAS unsigned char* lds, const int lda, const int ldb, const int K, const Sched& S, const Epi& E, int tid) {
;     ...
;             PG8_LDB(B0, 1, 0); PG8_LDB(B1, 1, 1); PG8_SCHED; PG8_LDA(At, 1, 0); PG8_STAGE(PG8_SA(0, 1), a2 + hA, voffA);
;             PG8_WAIT_V(8); PG8_WAIT_L(0); PG8_BAR; PG8_MMA(0, 0, At, B0); PG8_MMA(0, 1, At, B1); PG8_BAR; PG8_SCHED;
;             PG8_LDA(At, 1, 1); PG8_STAGE(PG8_SB(1, 0), b3, voffB); PG8_STAGE(PG8_SB(1, 1), b3 + hB, voffB); PG8_STAGE(PG8_SA(1, 0), a3, voffA);
;             PG8_WAIT_V(8); PG8_WAIT_L(0); PG8_BAR; PG8_MMA(1, 0, At, B0); PG8_MMA(1, 1, At, B1); PG8_BAR; PG8_SCHED;
;         }
;         if (wr == 0) PG8_BAR;
	s_add_i32 s16, 0, 0x18000
	v_add_u32_e32 v110, s16, v208
	s_add_i32 s17, 0, 0x1c000
	ds_read_b128 v[102:105], v110
	ds_read_b128 v[128:131], v110 offset:1024
	ds_read_b128 v[132:135], v110 offset:2048
	ds_read_b128 v[154:157], v110 offset:3072
	v_add_u32_e32 v110, s17, v208
	ds_read_b128 v[158:161], v110
	ds_read_b128 v[162:165], v110 offset:1024
	ds_read_b128 v[166:169], v110 offset:2048
	ds_read_b128 v[170:173], v110 offset:3072
	s_add_u32 s10, s10, 0x80000
	s_addc_u32 s11, s11, 0
	s_mov_b32 m0, s26
	ds_read_b128 v[174:177], v210 offset:32768
	ds_read_b128 v[178:181], v210 offset:33792
	ds_read_b128 v[182:185], v210 offset:34816
	ds_read_b128 v[186:189], v210 offset:35840
	ds_read_b128 v[190:193], v210 offset:36864
	ds_read_b128 v[194:197], v210 offset:37888
	ds_read_b128 v[200:203], v210 offset:38912
	ds_read_b128 v[204:207], v210 offset:39936
	global_load_lds_dwordx4 v144, s[10:11]
	s_mov_b32 m0, s27
	s_nop 0
	global_load_lds_dwordx4 v146, s[10:11]
	s_waitcnt vmcnt(8)
	s_waitcnt lgkmcnt(0)
	s_barrier
	s_setprio 1
	v_mfma_f32_16x16x32_bf16 v[140:143], v[102:105], v[174:177], v[140:143]
	v_mfma_f32_16x16x32_bf16 v[94:97], v[132:135], v[174:177], v[94:97]
	v_mfma_f32_16x16x32_bf16 v[136:139], v[102:105], v[182:185], v[136:139]
	v_mfma_f32_16x16x32_bf16 v[90:93], v[132:135], v[182:185], v[90:93]
	v_mfma_f32_16x16x32_bf16 v[124:127], v[102:105], v[190:193], v[124:127]
	v_mfma_f32_16x16x32_bf16 v[86:89], v[132:135], v[190:193], v[86:89]
	v_mfma_f32_16x16x32_bf16 v[120:123], v[102:105], v[200:203], v[120:123]
	v_mfma_f32_16x16x32_bf16 v[82:85], v[132:135], v[200:203], v[82:85]
	v_mfma_f32_16x16x32_bf16 v[140:143], v[128:131], v[178:181], v[140:143]
	v_mfma_f32_16x16x32_bf16 v[94:97], v[154:157], v[178:181], v[94:97]
	v_mfma_f32_16x16x32_bf16 v[136:139], v[128:131], v[186:189], v[136:139]
	v_mfma_f32_16x16x32_bf16 v[90:93], v[154:157], v[186:189], v[90:93]
	v_mfma_f32_16x16x32_bf16 v[124:127], v[128:131], v[194:197], v[124:127]
	v_mfma_f32_16x16x32_bf16 v[86:89], v[154:157], v[194:197], v[86:89]
	v_mfma_f32_16x16x32_bf16 v[120:123], v[128:131], v[204:207], v[120:123]
	v_mfma_f32_16x16x32_bf16 v[82:85], v[154:157], v[204:207], v[82:85]
	s_setprio 0
	s_setprio 1
	v_mfma_f32_16x16x32_bf16 v[62:65], v[158:161], v[174:177], v[62:65]
	v_mfma_f32_16x16x32_bf16 v[34:37], v[166:169], v[174:177], v[34:37]
	v_mfma_f32_16x16x32_bf16 v[58:61], v[158:161], v[182:185], v[58:61]
	v_mfma_f32_16x16x32_bf16 v[26:29], v[166:169], v[182:185], v[26:29]
	v_mfma_f32_16x16x32_bf16 v[54:57], v[158:161], v[190:193], v[54:57]
	v_mfma_f32_16x16x32_bf16 v[22:25], v[166:169], v[190:193], v[22:25]
	v_mfma_f32_16x16x32_bf16 v[50:53], v[158:161], v[200:203], v[50:53]
	v_mfma_f32_16x16x32_bf16 v[18:21], v[166:169], v[200:203], v[18:21]
	v_mfma_f32_16x16x32_bf16 v[62:65], v[162:165], v[178:181], v[62:65]
	v_mfma_f32_16x16x32_bf16 v[34:37], v[170:173], v[178:181], v[34:37]
	v_mfma_f32_16x16x32_bf16 v[58:61], v[162:165], v[186:189], v[58:61]
	v_mfma_f32_16x16x32_bf16 v[26:29], v[170:173], v[186:189], v[26:29]
	v_mfma_f32_16x16x32_bf16 v[54:57], v[162:165], v[194:197], v[54:57]
	v_mfma_f32_16x16x32_bf16 v[22:25], v[170:173], v[194:197], v[22:25]
	v_mfma_f32_16x16x32_bf16 v[50:53], v[162:165], v[204:207], v[50:53]
	v_mfma_f32_16x16x32_bf16 v[18:21], v[170:173], v[204:207], v[18:21]
	s_setprio 0
	s_barrier
	s_add_i32 s10, s16, s5
	s_mov_b32 m0, s10
	ds_read_b128 v[174:177], v210 offset:49152
	ds_read_b128 v[178:181], v210 offset:50176
	ds_read_b128 v[182:185], v210 offset:51200
	ds_read_b128 v[186:189], v210 offset:52224
	ds_read_b128 v[190:193], v210 offset:53248
	ds_read_b128 v[194:197], v210 offset:54272
	ds_read_b128 v[200:203], v210 offset:55296
	ds_read_b128 v[204:207], v210 offset:56320
	global_load_lds_dwordx4 v0, s[98:99]
	s_add_i32 m0, s10, 0x2000
	s_add_u32 s8, s8, 0x80080
	s_addc_u32 s9, s9, 0
	s_add_i32 s10, s17, s5
	global_load_lds_dwordx4 v148, s[98:99]
	s_mov_b32 m0, s10
	s_nop 0
	global_load_lds_dwordx4 v0, s[8:9]
	s_add_i32 m0, s10, 0x2000
	s_nop 0
	global_load_lds_dwordx4 v148, s[8:9]
	s_mov_b32 m0, s25
	s_nop 0
	global_load_lds_dwordx4 v144, s[100:101]
	s_mov_b32 m0, s56
	s_nop 0
	global_load_lds_dwordx4 v146, s[100:101]
	s_waitcnt vmcnt(8)
	s_waitcnt lgkmcnt(0)
	s_barrier
	s_setprio 1
	s_add_i32 s15, s15, 2
	s_add_u32 s6, s6, 0x100
	s_addc_u32 s7, s7, 0
	s_add_u32 s3, s3, 0x100
	s_addc_u32 s14, s14, 0
	s_cmp_gt_u32 s15, 29
	v_mfma_f32_16x16x32_bf16 v[116:119], v[102:105], v[174:177], v[116:119]
	v_mfma_f32_16x16x32_bf16 v[78:81], v[132:135], v[174:177], v[78:81]
	v_mfma_f32_16x16x32_bf16 v[110:113], v[102:105], v[182:185], v[112:115]
	v_mfma_f32_16x16x32_bf16 v[74:77], v[132:135], v[182:185], v[74:77]
	v_mfma_f32_16x16x32_bf16 v[106:109], v[102:105], v[190:193], v[106:109]
	v_mfma_f32_16x16x32_bf16 v[70:73], v[132:135], v[190:193], v[70:73]
	v_mfma_f32_16x16x32_bf16 v[98:101], v[102:105], v[200:203], v[98:101]
	v_mfma_f32_16x16x32_bf16 v[66:69], v[132:135], v[200:203], v[66:69]
	v_mfma_f32_16x16x32_bf16 v[116:119], v[128:131], v[178:181], v[116:119]
	v_mfma_f32_16x16x32_bf16 v[78:81], v[154:157], v[178:181], v[78:81]
	v_mfma_f32_16x16x32_bf16 v[112:115], v[128:131], v[186:189], v[110:113]
	v_mfma_f32_16x16x32_bf16 v[74:77], v[154:157], v[186:189], v[74:77]
	v_mfma_f32_16x16x32_bf16 v[108:111], v[128:131], v[194:197], v[106:109]
	v_mfma_f32_16x16x32_bf16 v[70:73], v[154:157], v[194:197], v[70:73]
	v_mfma_f32_16x16x32_bf16 v[98:101], v[128:131], v[204:207], v[98:101]
	v_mfma_f32_16x16x32_bf16 v[66:69], v[154:157], v[204:207], v[66:69]
	s_setprio 0
	s_setprio 1
	v_mfma_f32_16x16x32_bf16 v[46:49], v[158:161], v[174:177], v[46:49]
	v_mfma_f32_16x16x32_bf16 v[14:17], v[166:169], v[174:177], v[14:17]
	v_mfma_f32_16x16x32_bf16 v[42:45], v[158:161], v[182:185], v[42:45]
	v_mfma_f32_16x16x32_bf16 v[10:13], v[166:169], v[182:185], v[10:13]
	v_mfma_f32_16x16x32_bf16 v[38:41], v[158:161], v[190:193], v[38:41]
	v_mfma_f32_16x16x32_bf16 v[6:9], v[166:169], v[190:193], v[6:9]
	v_mfma_f32_16x16x32_bf16 v[30:33], v[158:161], v[200:203], v[30:33]
	v_mfma_f32_16x16x32_bf16 v[2:5], v[166:169], v[200:203], v[2:5]
	v_mfma_f32_16x16x32_bf16 v[46:49], v[162:165], v[178:181], v[46:49]
	v_mfma_f32_16x16x32_bf16 v[14:17], v[170:173], v[178:181], v[14:17]
	v_mfma_f32_16x16x32_bf16 v[42:45], v[162:165], v[186:189], v[42:45]
	v_mfma_f32_16x16x32_bf16 v[10:13], v[170:173], v[186:189], v[10:13]
	v_mfma_f32_16x16x32_bf16 v[38:41], v[162:165], v[194:197], v[38:41]
	v_mfma_f32_16x16x32_bf16 v[6:9], v[170:173], v[194:197], v[6:9]
	v_mfma_f32_16x16x32_bf16 v[30:33], v[162:165], v[204:207], v[30:33]
	v_mfma_f32_16x16x32_bf16 v[2:5], v[170:173], v[204:207], v[2:5]
	s_setprio 0
	s_barrier
	s_cbranch_scc0 .LBB0_530
	s_and_b64 vcc, exec, s[48:49]
	s_cbranch_vccz .LBB0_533
	s_barrier

; #define PG8_STAGE(bufoff, gbase, voff) do { _Pragma("unroll") for (int _i = 0; _i < 2; ++_i) \
;         __builtin_amdgcn_global_load_lds((const unsigned*)((const char*)(gbase) + (voff)[_i]), (LAS unsigned*)(lds + (bufoff) + ldsw + _i * 8192), 16, 0, 0); } while (0)
; #define PG8_LDA(dst, b, h) do { _Pragma("unroll") for (int m = 0; m < 4; ++m) _Pragma("unroll") for (int k = 0; k < 2; ++k) dst[m][k] = *(const LAS bf16x8*)(lds + PG8_SA(b, h) + aoff + m * 2048 + k * 1024); } while (0)
; #define PG8_LDB(dst, b, h) do { _Pragma("unroll") for (int n = 0; n < 2; ++n) _Pragma("unroll") for (int k = 0; k < 2; ++k) dst[n][k] = *(const LAS bf16x8*)(lds + PG8_SB(b, h) + boff + n * 2048 + k * 1024); } while (0)
; #define PG8_MMA(ai, bj, At, Bt) do { __builtin_amdgcn_s_setprio(1); _Pragma("unroll") for (int m = 0; m < 4; ++m) _Pragma("unroll") for (int n = 0; n < 2; ++n) _Pragma("unroll") for (int k = 0; k < 2; ++k) \
;         acc[ai][bj][m][n] = __builtin_amdgcn_mfma_f32_16x16x32_bf16(Bt[n][k], At[m][k], acc[ai][bj][m][n], 0, 0, 0); __builtin_amdgcn_s_setprio(0); } while (0)
; #define PG8_WAIT_V(n) asm volatile("s_waitcnt vmcnt(" #n ")" ::: "memory")
; #define PG8_WAIT_L(n) asm volatile("s_waitcnt lgkmcnt(" #n ")" ::: "memory")
; #define PG8_BAR __builtin_amdgcn_s_barrier()
; #define PG8_SCHED __builtin_amdgcn_sched_barrier(0)
; template <class Epi, class Sched>
; __device__ __forceinline__ void gemm_phase(LAS unsigned char* lds, const int lda, const int ldb, const int K, const Sched& S, const Epi& E, int tid) {
;     ...
;         for (int t = 0; t < nt; t += 2) {
;             const bool last = (t == nt - 2);
;             const char* a1 = cA + (size_t)(t + 1) * kstep;
;             const char* a2 = last ? nA : cA + (size_t)(t + 2) * kstep; const char* b2 = last ? nB : cB + (size_t)(t + 2) * kstep;
;             const char* a3 = a2 + kstep; const char* b3 = b2 + kstep;
;             PG8_LDB(B0, 0, 0); PG8_LDB(B1, 0, 1); PG8_SCHED; PG8_LDA(At, 0, 0); PG8_STAGE(PG8_SA(1, 1), a1 + hA, voffA);
;             PG8_WAIT_V(8); PG8_WAIT_L(0); PG8_BAR; PG8_MMA(0, 0, At, B0); PG8_MMA(0, 1, At, B1); PG8_BAR; PG8_SCHED;
;             PG8_LDA(At, 0, 1); PG8_STAGE(PG8_SB(0, 0), b2, voffB); PG8_STAGE(PG8_SB(0, 1), b2 + hB, voffB); PG8_STAGE(PG8_SA(0, 0), a2, voffA);
;             PG8_WAIT_V(8); PG8_WAIT_L(0); PG8_BAR; PG8_MMA(1, 0, At, B0); PG8_MMA(1, 1, At, B1); PG8_BAR; PG8_SCHED;
.LBB0_681:
	s_add_u32 s26, s56, 0xfff80080
	s_addc_u32 s27, s57, -1
	s_add_i32 s34, 0, 0x10000
	s_cmp_eq_u32 s60, 28
	s_cselect_b32 vcc_hi, s9, s27
	s_cselect_b32 vcc_lo, s8, s26
	v_add_u32_e32 v0, s34, v198
	s_cselect_b32 s27, s11, s19
	s_cselect_b32 s26, s10, s17
	s_add_i32 s76, 0, 0x14000
	ds_read_b128 v[114:117], v0
	ds_read_b128 v[118:121], v0 offset:1024
	ds_read_b128 v[122:125], v0 offset:2048
	ds_read_b128 v[126:129], v0 offset:3072
	v_add_u32_e32 v0, s76, v198
	ds_read_b128 v[130:133], v0
	ds_read_b128 v[134:137], v0 offset:1024
	ds_read_b128 v[138:141], v0 offset:2048
	ds_read_b128 v[142:145], v0 offset:3072
	s_add_i32 m0, s29, 0xc000
	ds_read_b128 v[162:165], v237
	ds_read_b128 v[166:169], v237 offset:1024
	ds_read_b128 v[202:205], v237 offset:2048
	ds_read_b128 v[206:209], v237 offset:3072
	ds_read_b128 v[210:213], v237 offset:4096
	ds_read_b128 v[214:217], v237 offset:5120
	ds_read_b128 v[218:221], v237 offset:6144
	ds_read_b128 v[240:243], v237 offset:7168
	global_load_lds_dwordx4 v196, s[56:57]
	s_add_i32 m0, s29, 0xe000
	s_nop 0
	global_load_lds_dwordx4 v200, s[56:57]
	s_waitcnt vmcnt(8)
	s_waitcnt lgkmcnt(0)
	s_barrier
	s_setprio 1
	v_mfma_f32_16x16x32_bf16 v[158:161], v[114:117], v[162:165], v[158:161]
	v_mfma_f32_16x16x32_bf16 v[62:65], v[122:125], v[162:165], v[62:65]
	v_mfma_f32_16x16x32_bf16 v[150:153], v[114:117], v[202:205], v[150:153]
	v_mfma_f32_16x16x32_bf16 v[54:57], v[122:125], v[202:205], v[54:57]
	v_mfma_f32_16x16x32_bf16 v[110:113], v[114:117], v[210:213], v[110:113]
	v_mfma_f32_16x16x32_bf16 v[46:49], v[122:125], v[210:213], v[46:49]
	v_mfma_f32_16x16x32_bf16 v[102:105], v[114:117], v[218:221], v[102:105]
	v_mfma_f32_16x16x32_bf16 v[38:41], v[122:125], v[218:221], v[38:41]
	v_mfma_f32_16x16x32_bf16 v[158:161], v[118:121], v[166:169], v[158:161]
	v_mfma_f32_16x16x32_bf16 v[62:65], v[126:129], v[166:169], v[62:65]
	v_mfma_f32_16x16x32_bf16 v[150:153], v[118:121], v[206:209], v[150:153]
	v_mfma_f32_16x16x32_bf16 v[54:57], v[126:129], v[206:209], v[54:57]
	v_mfma_f32_16x16x32_bf16 v[110:113], v[118:121], v[214:217], v[110:113]
	v_mfma_f32_16x16x32_bf16 v[46:49], v[126:129], v[214:217], v[46:49]
	v_mfma_f32_16x16x32_bf16 v[102:105], v[118:121], v[240:243], v[102:105]
	v_mfma_f32_16x16x32_bf16 v[38:41], v[126:129], v[240:243], v[38:41]
	s_setprio 0
	s_setprio 1
	v_mfma_f32_16x16x32_bf16 v[154:157], v[130:133], v[162:165], v[154:157]
	v_mfma_f32_16x16x32_bf16 v[58:61], v[138:141], v[162:165], v[58:61]
	v_mfma_f32_16x16x32_bf16 v[146:149], v[130:133], v[202:205], v[146:149]
	v_mfma_f32_16x16x32_bf16 v[50:53], v[138:141], v[202:205], v[50:53]
	v_mfma_f32_16x16x32_bf16 v[106:109], v[130:133], v[210:213], v[106:109]
	v_mfma_f32_16x16x32_bf16 v[42:45], v[138:141], v[210:213], v[42:45]
	v_mfma_f32_16x16x32_bf16 v[98:101], v[130:133], v[218:221], v[98:101]
	v_mfma_f32_16x16x32_bf16 v[34:37], v[138:141], v[218:221], v[34:37]
	v_mfma_f32_16x16x32_bf16 v[154:157], v[134:137], v[166:169], v[154:157]
	v_mfma_f32_16x16x32_bf16 v[58:61], v[142:145], v[166:169], v[58:61]
	v_mfma_f32_16x16x32_bf16 v[146:149], v[134:137], v[206:209], v[146:149]
	v_mfma_f32_16x16x32_bf16 v[50:53], v[142:145], v[206:209], v[50:53]
	v_mfma_f32_16x16x32_bf16 v[106:109], v[134:137], v[214:217], v[106:109]
	v_mfma_f32_16x16x32_bf16 v[42:45], v[142:145], v[214:217], v[42:45]
	v_mfma_f32_16x16x32_bf16 v[98:101], v[134:137], v[240:243], v[98:101]
	v_mfma_f32_16x16x32_bf16 v[34:37], v[142:145], v[240:243], v[34:37]
	s_setprio 0
	s_barrier
	s_add_i32 s34, s34, s28
	s_mov_b32 m0, s34
	ds_read_b128 v[162:165], v237 offset:16384
	ds_read_b128 v[166:169], v237 offset:17408
	ds_read_b128 v[202:205], v237 offset:18432
	ds_read_b128 v[206:209], v237 offset:19456
	ds_read_b128 v[210:213], v237 offset:20480
	ds_read_b128 v[214:217], v237 offset:21504
	ds_read_b128 v[218:221], v237 offset:22528
	ds_read_b128 v[240:243], v237 offset:23552
	global_load_lds_dwordx4 v172, s[26:27]
	s_add_i32 m0, s34, 0x2000
	s_add_u32 s34, s26, 0x80000
	s_addc_u32 s35, s27, 0
	s_add_i32 s76, s76, s28
	global_load_lds_dwordx4 v176, s[26:27]
	s_mov_b32 m0, s76
	s_nop 0
	global_load_lds_dwordx4 v172, s[34:35]
	s_add_i32 m0, s76, 0x2000
	s_nop 0
	global_load_lds_dwordx4 v176, s[34:35]
	s_mov_b32 m0, s29
	s_nop 0
	global_load_lds_dwordx4 v170, vcc
	s_mov_b32 m0, s67
	s_nop 0
	global_load_lds_dwordx4 v174, vcc
	s_waitcnt vmcnt(8)
	s_waitcnt lgkmcnt(0)
	s_barrier
	s_setprio 1
	v_mfma_f32_16x16x32_bf16 v[94:97], v[114:117], v[162:165], v[94:97]
	v_mfma_f32_16x16x32_bf16 v[30:33], v[122:125], v[162:165], v[30:33]
	v_mfma_f32_16x16x32_bf16 v[86:89], v[114:117], v[202:205], v[86:89]
	v_mfma_f32_16x16x32_bf16 v[22:25], v[122:125], v[202:205], v[22:25]
	v_mfma_f32_16x16x32_bf16 v[78:81], v[114:117], v[210:213], v[78:81]
	v_mfma_f32_16x16x32_bf16 v[14:17], v[122:125], v[210:213], v[14:17]
	v_mfma_f32_16x16x32_bf16 v[70:73], v[114:117], v[218:221], v[70:73]
	v_mfma_f32_16x16x32_bf16 v[6:9], v[122:125], v[218:221], v[6:9]
	v_mfma_f32_16x16x32_bf16 v[94:97], v[118:121], v[166:169], v[94:97]
	v_mfma_f32_16x16x32_bf16 v[30:33], v[126:129], v[166:169], v[30:33]
	v_mfma_f32_16x16x32_bf16 v[86:89], v[118:121], v[206:209], v[86:89]
	v_mfma_f32_16x16x32_bf16 v[22:25], v[126:129], v[206:209], v[22:25]
	v_mfma_f32_16x16x32_bf16 v[78:81], v[118:121], v[214:217], v[78:81]
	v_mfma_f32_16x16x32_bf16 v[14:17], v[126:129], v[214:217], v[14:17]
	v_mfma_f32_16x16x32_bf16 v[70:73], v[118:121], v[240:243], v[70:73]
	v_mfma_f32_16x16x32_bf16 v[6:9], v[126:129], v[240:243], v[6:9]
	s_setprio 0
	s_setprio 1
	v_mfma_f32_16x16x32_bf16 v[90:93], v[130:133], v[162:165], v[90:93]
	v_mfma_f32_16x16x32_bf16 v[26:29], v[138:141], v[162:165], v[26:29]
	v_mfma_f32_16x16x32_bf16 v[82:85], v[130:133], v[202:205], v[82:85]
	v_mfma_f32_16x16x32_bf16 v[18:21], v[138:141], v[202:205], v[18:21]
	v_mfma_f32_16x16x32_bf16 v[74:77], v[130:133], v[210:213], v[74:77]
	v_mfma_f32_16x16x32_bf16 v[10:13], v[138:141], v[210:213], v[10:13]
	v_mfma_f32_16x16x32_bf16 v[66:69], v[130:133], v[218:221], v[66:69]
	v_mfma_f32_16x16x32_bf16 v[2:5], v[138:141], v[218:221], v[2:5]
	v_mfma_f32_16x16x32_bf16 v[90:93], v[134:137], v[166:169], v[90:93]
	v_mfma_f32_16x16x32_bf16 v[26:29], v[142:145], v[166:169], v[26:29]
	v_mfma_f32_16x16x32_bf16 v[82:85], v[134:137], v[206:209], v[82:85]
	v_mfma_f32_16x16x32_bf16 v[18:21], v[142:145], v[206:209], v[18:21]
	v_mfma_f32_16x16x32_bf16 v[74:77], v[134:137], v[214:217], v[74:77]
	v_mfma_f32_16x16x32_bf16 v[10:13], v[142:145], v[214:217], v[10:13]
	v_mfma_f32_16x16x32_bf16 v[66:69], v[134:137], v[240:243], v[66:69]
	v_mfma_f32_16x16x32_bf16 v[2:5], v[142:145], v[240:243], v[2:5]
	s_setprio 0
	s_barrier
; #define PG8_STAGE(bufoff, gbase, voff) do { _Pragma("unroll") for (int _i = 0; _i < 2; ++_i) \
;         __builtin_amdgcn_global_load_lds((const unsigned*)((const char*)(gbase) + (voff)[_i]), (LAS unsigned*)(lds + (bufoff) + ldsw + _i * 8192), 16, 0, 0); } while (0)
; #define PG8_LDA(dst, b, h) do { _Pragma("unroll") for (int m = 0; m < 4; ++m) _Pragma("unroll") for (int k = 0; k < 2; ++k) dst[m][k] = *(const LAS bf16x8*)(lds + PG8_SA(b, h) + aoff + m * 2048 + k * 1024); } while (0)
; #define PG8_LDB(dst, b, h) do { _Pragma("unroll") for (int n = 0; n < 2; ++n) _Pragma("unroll") for (int k = 0; k < 2; ++k) dst[n][k] = *(const LAS bf16x8*)(lds + PG8_SB(b, h) + boff + n * 2048 + k * 1024); } while (0)
; #define PG8_MMA(ai, bj, At, Bt) do { __builtin_amdgcn_s_setprio(1); _Pragma("unroll") for (int m = 0; m < 4; ++m) _Pragma("unroll") for (int n = 0; n < 2; ++n) _Pragma("unroll") for (int k = 0; k < 2; ++k) \
;         acc[ai][bj][m][n] = __builtin_amdgcn_mfma_f32_16x16x32_bf16(Bt[n][k], At[m][k], acc[ai][bj][m][n], 0, 0, 0); __builtin_amdgcn_s_setprio(0); } while (0)
; #define PG8_WAIT_V(n) asm volatile("s_waitcnt vmcnt(" #n ")" ::: "memory")
; #define PG8_WAIT_L(n) asm volatile("s_waitcnt lgkmcnt(" #n ")" ::: "memory")
; #define PG8_BAR __builtin_amdgcn_s_barrier()
; #define PG8_SCHED __builtin_amdgcn_sched_barrier(0)
; template <class Epi, class Sched>
; __device__ __forceinline__ void gemm_phase(LAS unsigned char* lds, const int lda, const int ldb, const int K, const Sched& S, const Epi& E, int tid) {
;     ...
;             PG8_LDB(B0, 1, 0); PG8_LDB(B1, 1, 1); PG8_SCHED; PG8_LDA(At, 1, 0); PG8_STAGE(PG8_SA(0, 1), a2 + hA, voffA);
;             PG8_WAIT_V(8); PG8_WAIT_L(0); PG8_BAR; PG8_MMA(0, 0, At, B0); PG8_MMA(0, 1, At, B1); PG8_BAR; PG8_SCHED;
;             PG8_LDA(At, 1, 1); PG8_STAGE(PG8_SB(1, 0), b3, voffB); PG8_STAGE(PG8_SB(1, 1), b3 + hB, voffB); PG8_STAGE(PG8_SA(1, 0), a3, voffA);
;             PG8_WAIT_V(8); PG8_WAIT_L(0); PG8_BAR; PG8_MMA(1, 0, At, B0); PG8_MMA(1, 1, At, B1); PG8_BAR; PG8_SCHED;
;         }
;         if (wr == 0) PG8_BAR;
	s_add_i32 s76, 0, 0x18000
	v_add_u32_e32 v0, s76, v198
	s_add_i32 s94, 0, 0x1c000
	ds_read_b128 v[114:117], v0
	ds_read_b128 v[118:121], v0 offset:1024
	ds_read_b128 v[122:125], v0 offset:2048
	ds_read_b128 v[126:129], v0 offset:3072
	v_add_u32_e32 v0, s94, v198
	ds_read_b128 v[130:133], v0
	ds_read_b128 v[134:137], v0 offset:1024
	ds_read_b128 v[138:141], v0 offset:2048
	ds_read_b128 v[142:145], v0 offset:3072
	s_add_u32 s34, vcc_lo, 0x80000
	s_addc_u32 s35, vcc_hi, 0
	s_mov_b32 m0, s25
	ds_read_b128 v[162:165], v237 offset:32768
	ds_read_b128 v[166:169], v237 offset:33792
	ds_read_b128 v[202:205], v237 offset:34816
	ds_read_b128 v[206:209], v237 offset:35840
	ds_read_b128 v[210:213], v237 offset:36864
	ds_read_b128 v[214:217], v237 offset:37888
	ds_read_b128 v[218:221], v237 offset:38912
	ds_read_b128 v[240:243], v237 offset:39936
	global_load_lds_dwordx4 v170, s[34:35]
	s_mov_b32 m0, s0
	s_nop 0
	global_load_lds_dwordx4 v174, s[34:35]
	s_waitcnt vmcnt(8)
	s_waitcnt lgkmcnt(0)
	s_barrier
	s_setprio 1
	v_mfma_f32_16x16x32_bf16 v[158:161], v[114:117], v[162:165], v[158:161]
	v_mfma_f32_16x16x32_bf16 v[62:65], v[122:125], v[162:165], v[62:65]
	v_mfma_f32_16x16x32_bf16 v[150:153], v[114:117], v[202:205], v[150:153]
	v_mfma_f32_16x16x32_bf16 v[54:57], v[122:125], v[202:205], v[54:57]
	v_mfma_f32_16x16x32_bf16 v[110:113], v[114:117], v[210:213], v[110:113]
	v_mfma_f32_16x16x32_bf16 v[46:49], v[122:125], v[210:213], v[46:49]
	v_mfma_f32_16x16x32_bf16 v[102:105], v[114:117], v[218:221], v[102:105]
	v_mfma_f32_16x16x32_bf16 v[38:41], v[122:125], v[218:221], v[38:41]
	v_mfma_f32_16x16x32_bf16 v[158:161], v[118:121], v[166:169], v[158:161]
	v_mfma_f32_16x16x32_bf16 v[62:65], v[126:129], v[166:169], v[62:65]
	v_mfma_f32_16x16x32_bf16 v[150:153], v[118:121], v[206:209], v[150:153]
	v_mfma_f32_16x16x32_bf16 v[54:57], v[126:129], v[206:209], v[54:57]
	v_mfma_f32_16x16x32_bf16 v[110:113], v[118:121], v[214:217], v[110:113]
	v_mfma_f32_16x16x32_bf16 v[46:49], v[126:129], v[214:217], v[46:49]
	v_mfma_f32_16x16x32_bf16 v[102:105], v[118:121], v[240:243], v[102:105]
	v_mfma_f32_16x16x32_bf16 v[38:41], v[126:129], v[240:243], v[38:41]
	s_setprio 0
	s_setprio 1
	v_mfma_f32_16x16x32_bf16 v[154:157], v[130:133], v[162:165], v[154:157]
	v_mfma_f32_16x16x32_bf16 v[58:61], v[138:141], v[162:165], v[58:61]
	v_mfma_f32_16x16x32_bf16 v[146:149], v[130:133], v[202:205], v[146:149]
	v_mfma_f32_16x16x32_bf16 v[50:53], v[138:141], v[202:205], v[50:53]
	v_mfma_f32_16x16x32_bf16 v[106:109], v[130:133], v[210:213], v[106:109]
	v_mfma_f32_16x16x32_bf16 v[42:45], v[138:141], v[210:213], v[42:45]
	v_mfma_f32_16x16x32_bf16 v[98:101], v[130:133], v[218:221], v[98:101]
	v_mfma_f32_16x16x32_bf16 v[34:37], v[138:141], v[218:221], v[34:37]
	v_mfma_f32_16x16x32_bf16 v[154:157], v[134:137], v[166:169], v[154:157]
	v_mfma_f32_16x16x32_bf16 v[58:61], v[142:145], v[166:169], v[58:61]
	v_mfma_f32_16x16x32_bf16 v[146:149], v[134:137], v[206:209], v[146:149]
	v_mfma_f32_16x16x32_bf16 v[50:53], v[142:145], v[206:209], v[50:53]
	v_mfma_f32_16x16x32_bf16 v[106:109], v[134:137], v[214:217], v[106:109]
	v_mfma_f32_16x16x32_bf16 v[42:45], v[142:145], v[214:217], v[42:45]
	v_mfma_f32_16x16x32_bf16 v[98:101], v[134:137], v[240:243], v[98:101]
	v_mfma_f32_16x16x32_bf16 v[34:37], v[142:145], v[240:243], v[34:37]
	s_setprio 0
	s_barrier
	s_add_i32 s34, s76, s28
	s_add_u32 s98, s26, s30
	s_addc_u32 s99, s27, s31
	s_mov_b32 m0, s34
	ds_read_b128 v[162:165], v237 offset:49152
	ds_read_b128 v[166:169], v237 offset:50176
	ds_read_b128 v[202:205], v237 offset:51200
	ds_read_b128 v[206:209], v237 offset:52224
	ds_read_b128 v[210:213], v237 offset:53248
	ds_read_b128 v[214:217], v237 offset:54272
	ds_read_b128 v[218:221], v237 offset:55296
	ds_read_b128 v[240:243], v237 offset:56320
	global_load_lds_dwordx4 v172, s[98:99]
	s_add_i32 m0, s34, 0x2000
	s_add_u32 s26, s26, 0x80080
	s_addc_u32 s27, s27, 0
	s_add_i32 s34, s94, s28
	global_load_lds_dwordx4 v176, s[98:99]
	s_mov_b32 m0, s34
	s_nop 0
	global_load_lds_dwordx4 v172, s[26:27]
	s_add_i32 m0, s34, 0x2000
	s_nop 0
	global_load_lds_dwordx4 v176, s[26:27]
	s_add_u32 s100, vcc_lo, s30
	s_addc_u32 s101, vcc_hi, s31
	s_mov_b32 m0, s22
	s_nop 0
	global_load_lds_dwordx4 v170, s[100:101]
	s_mov_b32 m0, s23
	s_nop 0
	global_load_lds_dwordx4 v174, s[100:101]
	s_waitcnt vmcnt(8)
	s_waitcnt lgkmcnt(0)
	s_barrier
	s_setprio 1
	s_add_i32 s60, s60, 2
	s_add_u32 s56, s56, 0x100
	s_addc_u32 s57, s57, 0
	s_add_u32 s17, s17, 0x100
	s_addc_u32 s19, s19, 0
	s_cmp_gt_u32 s60, 29
	v_mfma_f32_16x16x32_bf16 v[94:97], v[114:117], v[162:165], v[94:97]
	v_mfma_f32_16x16x32_bf16 v[30:33], v[122:125], v[162:165], v[30:33]
	v_mfma_f32_16x16x32_bf16 v[86:89], v[114:117], v[202:205], v[86:89]
	v_mfma_f32_16x16x32_bf16 v[22:25], v[122:125], v[202:205], v[22:25]
	v_mfma_f32_16x16x32_bf16 v[78:81], v[114:117], v[210:213], v[78:81]
	v_mfma_f32_16x16x32_bf16 v[14:17], v[122:125], v[210:213], v[14:17]
	v_mfma_f32_16x16x32_bf16 v[70:73], v[114:117], v[218:221], v[70:73]
	v_mfma_f32_16x16x32_bf16 v[6:9], v[122:125], v[218:221], v[6:9]
	v_mfma_f32_16x16x32_bf16 v[94:97], v[118:121], v[166:169], v[94:97]
	v_mfma_f32_16x16x32_bf16 v[30:33], v[126:129], v[166:169], v[30:33]
	v_mfma_f32_16x16x32_bf16 v[86:89], v[118:121], v[206:209], v[86:89]
	v_mfma_f32_16x16x32_bf16 v[22:25], v[126:129], v[206:209], v[22:25]
	v_mfma_f32_16x16x32_bf16 v[78:81], v[118:121], v[214:217], v[78:81]
	v_mfma_f32_16x16x32_bf16 v[14:17], v[126:129], v[214:217], v[14:17]
	v_mfma_f32_16x16x32_bf16 v[70:73], v[118:121], v[240:243], v[70:73]
	v_mfma_f32_16x16x32_bf16 v[6:9], v[126:129], v[240:243], v[6:9]
	s_setprio 0
	s_setprio 1
	v_mfma_f32_16x16x32_bf16 v[90:93], v[130:133], v[162:165], v[90:93]
	v_mfma_f32_16x16x32_bf16 v[26:29], v[138:141], v[162:165], v[26:29]
	v_mfma_f32_16x16x32_bf16 v[82:85], v[130:133], v[202:205], v[82:85]
	v_mfma_f32_16x16x32_bf16 v[18:21], v[138:141], v[202:205], v[18:21]
	v_mfma_f32_16x16x32_bf16 v[74:77], v[130:133], v[210:213], v[74:77]
	v_mfma_f32_16x16x32_bf16 v[10:13], v[138:141], v[210:213], v[10:13]
	v_mfma_f32_16x16x32_bf16 v[66:69], v[130:133], v[218:221], v[66:69]
	v_mfma_f32_16x16x32_bf16 v[2:5], v[138:141], v[218:221], v[2:5]
	v_mfma_f32_16x16x32_bf16 v[90:93], v[134:137], v[166:169], v[90:93]
	v_mfma_f32_16x16x32_bf16 v[26:29], v[142:145], v[166:169], v[26:29]
	v_mfma_f32_16x16x32_bf16 v[82:85], v[134:137], v[206:209], v[82:85]
	v_mfma_f32_16x16x32_bf16 v[18:21], v[142:145], v[206:209], v[18:21]
	v_mfma_f32_16x16x32_bf16 v[74:77], v[134:137], v[214:217], v[74:77]
	v_mfma_f32_16x16x32_bf16 v[10:13], v[142:145], v[214:217], v[10:13]
	v_mfma_f32_16x16x32_bf16 v[66:69], v[134:137], v[240:243], v[66:69]
	v_mfma_f32_16x16x32_bf16 v[2:5], v[142:145], v[240:243], v[2:5]
	s_setprio 0
	s_barrier
	s_cbranch_scc0 .LBB0_681
	s_and_b64 vcc, exec, s[90:91]
	s_cbranch_vccz .LBB0_686
	s_barrier
	s_and_saveexec_b64 s[26:27], s[40:41]
	s_movk_i32 s60, 0x2c00
	s_cbranch_execnz .LBB0_687

; #define PG8_STAGE(bufoff, gbase, voff) do { _Pragma("unroll") for (int _i = 0; _i < 2; ++_i) \
;         __builtin_amdgcn_global_load_lds((const unsigned*)((const char*)(gbase) + (voff)[_i]), (LAS unsigned*)(lds + (bufoff) + ldsw + _i * 8192), 16, 0, 0); } while (0)
; #define PG8_LDA(dst, b, h) do { _Pragma("unroll") for (int m = 0; m < 4; ++m) _Pragma("unroll") for (int k = 0; k < 2; ++k) dst[m][k] = *(const LAS bf16x8*)(lds + PG8_SA(b, h) + aoff + m * 2048 + k * 1024); } while (0)
; #define PG8_LDB(dst, b, h) do { _Pragma("unroll") for (int n = 0; n < 2; ++n) _Pragma("unroll") for (int k = 0; k < 2; ++k) dst[n][k] = *(const LAS bf16x8*)(lds + PG8_SB(b, h) + boff + n * 2048 + k * 1024); } while (0)
; #define PG8_MMA(ai, bj, At, Bt) do { __builtin_amdgcn_s_setprio(1); _Pragma("unroll") for (int m = 0; m < 4; ++m) _Pragma("unroll") for (int n = 0; n < 2; ++n) _Pragma("unroll") for (int k = 0; k < 2; ++k) \
;         acc[ai][bj][m][n] = __builtin_amdgcn_mfma_f32_16x16x32_bf16(Bt[n][k], At[m][k], acc[ai][bj][m][n], 0, 0, 0); __builtin_amdgcn_s_setprio(0); } while (0)
; #define PG8_WAIT_V(n) asm volatile("s_waitcnt vmcnt(" #n ")" ::: "memory")
; #define PG8_WAIT_L(n) asm volatile("s_waitcnt lgkmcnt(" #n ")" ::: "memory")
; #define PG8_BAR __builtin_amdgcn_s_barrier()
; #define PG8_SCHED __builtin_amdgcn_sched_barrier(0)
; template <class Epi, class Sched>
; __device__ __forceinline__ void gemm_phase(LAS unsigned char* lds, const int lda, const int ldb, const int K, const Sched& S, const Epi& E, int tid) {
;     ...
;         for (int t = 0; t < nt; t += 2) {
;             const bool last = (t == nt - 2);
;             const char* a1 = cA + (size_t)(t + 1) * kstep;
;             const char* a2 = last ? nA : cA + (size_t)(t + 2) * kstep; const char* b2 = last ? nB : cB + (size_t)(t + 2) * kstep;
;             const char* a3 = a2 + kstep; const char* b3 = b2 + kstep;
;             PG8_LDB(B0, 0, 0); PG8_LDB(B1, 0, 1); PG8_SCHED; PG8_LDA(At, 0, 0); PG8_STAGE(PG8_SA(1, 1), a1 + hA, voffA);
;             PG8_WAIT_V(8); PG8_WAIT_L(0); PG8_BAR; PG8_MMA(0, 0, At, B0); PG8_MMA(0, 1, At, B1); PG8_BAR; PG8_SCHED;
;             PG8_LDA(At, 0, 1); PG8_STAGE(PG8_SB(0, 0), b2, voffB); PG8_STAGE(PG8_SB(0, 1), b2 + hB, voffB); PG8_STAGE(PG8_SA(0, 0), a2, voffA);
;             PG8_WAIT_V(8); PG8_WAIT_L(0); PG8_BAR; PG8_MMA(1, 0, At, B0); PG8_MMA(1, 1, At, B1); PG8_BAR; PG8_SCHED;
.LBB0_880:
	s_add_u32 s4, s2, 0x100
	s_addc_u32 s5, s3, 0
	s_add_i32 s33, 0, 0x10000
	s_cmpk_eq_i32 s29, 0x54
	s_cselect_b32 s9, s49, s5
	s_cselect_b32 s8, s48, s4
	s_cselect_b32 s7, s51, s28
	s_cselect_b32 s6, s50, s25
	s_add_i32 s34, 0, 0x14000
	v_add_u32_e32 v130, s33, v208
	v_add_u32_e32 v168, s34, v208
	ds_read_b128 v[82:85], v130
	ds_read_b128 v[86:89], v130 offset:1024
	ds_read_b128 v[126:129], v130 offset:2048
	ds_read_b128 v[130:133], v130 offset:3072
	ds_read_b128 v[156:159], v168
	ds_read_b128 v[160:163], v168 offset:1024
	ds_read_b128 v[164:167], v168 offset:2048
	ds_read_b128 v[168:171], v168 offset:3072
	s_add_i32 m0, s15, 0xc000
	ds_read_b128 v[172:175], v210
	ds_read_b128 v[176:179], v210 offset:1024
	ds_read_b128 v[180:183], v210 offset:2048
	ds_read_b128 v[184:187], v210 offset:3072
	ds_read_b128 v[188:191], v210 offset:4096
	ds_read_b128 v[192:195], v210 offset:5120
	ds_read_b128 v[200:203], v210 offset:6144
	ds_read_b128 v[204:207], v210 offset:7168
	global_load_lds_dwordx4 v152, s[2:3]
	s_add_i32 m0, s15, 0xe000
	s_nop 0
	global_load_lds_dwordx4 v154, s[2:3]
	s_waitcnt vmcnt(8)
	s_waitcnt lgkmcnt(0)
	s_barrier
	s_setprio 1
	v_mfma_f32_16x16x32_bf16 v[142:145], v[82:85], v[172:175], v[142:145]
	v_mfma_f32_16x16x32_bf16 v[102:105], v[126:129], v[172:175], v[102:105]
	v_mfma_f32_16x16x32_bf16 v[138:141], v[82:85], v[180:183], v[138:141]
	v_mfma_f32_16x16x32_bf16 v[98:101], v[126:129], v[180:183], v[98:101]
	v_mfma_f32_16x16x32_bf16 v[134:137], v[82:85], v[188:191], v[134:137]
	v_mfma_f32_16x16x32_bf16 v[94:97], v[126:129], v[188:191], v[94:97]
	v_mfma_f32_16x16x32_bf16 v[122:125], v[82:85], v[200:203], v[122:125]
	v_mfma_f32_16x16x32_bf16 v[90:93], v[126:129], v[200:203], v[90:93]
	v_mfma_f32_16x16x32_bf16 v[142:145], v[86:89], v[176:179], v[142:145]
	v_mfma_f32_16x16x32_bf16 v[102:105], v[130:133], v[176:179], v[102:105]
	v_mfma_f32_16x16x32_bf16 v[138:141], v[86:89], v[184:187], v[138:141]
	v_mfma_f32_16x16x32_bf16 v[98:101], v[130:133], v[184:187], v[98:101]
	v_mfma_f32_16x16x32_bf16 v[134:137], v[86:89], v[192:195], v[134:137]
	v_mfma_f32_16x16x32_bf16 v[94:97], v[130:133], v[192:195], v[94:97]
	v_mfma_f32_16x16x32_bf16 v[122:125], v[86:89], v[204:207], v[122:125]
	v_mfma_f32_16x16x32_bf16 v[90:93], v[130:133], v[204:207], v[90:93]
	s_setprio 0
	s_setprio 1
	v_mfma_f32_16x16x32_bf16 v[66:69], v[156:159], v[172:175], v[66:69]
	v_mfma_f32_16x16x32_bf16 v[34:37], v[164:167], v[172:175], v[34:37]
	v_mfma_f32_16x16x32_bf16 v[58:61], v[156:159], v[180:183], v[58:61]
	v_mfma_f32_16x16x32_bf16 v[26:29], v[164:167], v[180:183], v[26:29]
	v_mfma_f32_16x16x32_bf16 v[54:57], v[156:159], v[188:191], v[54:57]
	v_mfma_f32_16x16x32_bf16 v[22:25], v[164:167], v[188:191], v[22:25]
	v_mfma_f32_16x16x32_bf16 v[50:53], v[156:159], v[200:203], v[50:53]
	v_mfma_f32_16x16x32_bf16 v[18:21], v[164:167], v[200:203], v[18:21]
	v_mfma_f32_16x16x32_bf16 v[66:69], v[160:163], v[176:179], v[66:69]
	v_mfma_f32_16x16x32_bf16 v[34:37], v[168:171], v[176:179], v[34:37]
	v_mfma_f32_16x16x32_bf16 v[58:61], v[160:163], v[184:187], v[58:61]
	v_mfma_f32_16x16x32_bf16 v[26:29], v[168:171], v[184:187], v[26:29]
	v_mfma_f32_16x16x32_bf16 v[54:57], v[160:163], v[192:195], v[54:57]
	v_mfma_f32_16x16x32_bf16 v[22:25], v[168:171], v[192:195], v[22:25]
	v_mfma_f32_16x16x32_bf16 v[50:53], v[160:163], v[204:207], v[50:53]
	v_mfma_f32_16x16x32_bf16 v[18:21], v[168:171], v[204:207], v[18:21]
	s_setprio 0
	s_barrier
	s_add_u32 s98, s6, s30
	s_addc_u32 s99, s7, s31
	s_add_u32 s100, s8, s30
	s_addc_u32 s101, s9, s31
	s_add_i32 s2, s33, s14
	s_mov_b32 m0, s2
	ds_read_b128 v[172:175], v210 offset:16384
	ds_read_b128 v[176:179], v210 offset:17408
	ds_read_b128 v[180:183], v210 offset:18432
	ds_read_b128 v[184:187], v210 offset:19456
	ds_read_b128 v[188:191], v210 offset:20480
	ds_read_b128 v[192:195], v210 offset:21504
	ds_read_b128 v[200:203], v210 offset:22528
	ds_read_b128 v[204:207], v210 offset:23552
	global_load_lds_dwordx4 v0, s[6:7]
	s_add_i32 m0, s2, 0x2000
	s_add_u32 s2, s6, 0x160000
	s_addc_u32 s3, s7, 0
	s_add_i32 s33, s34, s14
	global_load_lds_dwordx4 v150, s[6:7]
	s_mov_b32 m0, s33
	s_nop 0
	global_load_lds_dwordx4 v0, s[2:3]
	s_add_i32 m0, s33, 0x2000
	s_nop 0
	global_load_lds_dwordx4 v150, s[2:3]
	s_mov_b32 m0, s15
	s_nop 0
	global_load_lds_dwordx4 v146, s[8:9]
	s_mov_b32 m0, s16
	s_nop 0
	global_load_lds_dwordx4 v148, s[8:9]
	s_waitcnt vmcnt(8)
	s_waitcnt lgkmcnt(0)
	s_barrier
	s_setprio 1
	v_mfma_f32_16x16x32_bf16 v[118:121], v[82:85], v[172:175], v[118:121]
	v_mfma_f32_16x16x32_bf16 v[78:81], v[126:129], v[172:175], v[78:81]
	v_mfma_f32_16x16x32_bf16 v[114:117], v[82:85], v[180:183], v[114:117]
	v_mfma_f32_16x16x32_bf16 v[74:77], v[126:129], v[180:183], v[74:77]
	v_mfma_f32_16x16x32_bf16 v[110:113], v[82:85], v[188:191], v[110:113]
	v_mfma_f32_16x16x32_bf16 v[70:73], v[126:129], v[188:191], v[70:73]
	v_mfma_f32_16x16x32_bf16 v[62:65], v[126:129], v[200:203], v[62:65]
	v_mfma_f32_16x16x32_bf16 v[118:121], v[86:89], v[176:179], v[118:121]
	v_mfma_f32_16x16x32_bf16 v[78:81], v[130:133], v[176:179], v[78:81]
	v_mfma_f32_16x16x32_bf16 v[114:117], v[86:89], v[184:187], v[114:117]
	v_mfma_f32_16x16x32_bf16 v[74:77], v[130:133], v[184:187], v[74:77]
	v_mfma_f32_16x16x32_bf16 v[110:113], v[86:89], v[192:195], v[110:113]
	v_mfma_f32_16x16x32_bf16 v[70:73], v[130:133], v[192:195], v[70:73]
	v_mfma_f32_16x16x32_bf16 v[82:85], v[82:85], v[200:203], v[106:109]
	v_mfma_f32_16x16x32_bf16 v[62:65], v[130:133], v[204:207], v[62:65]
	v_mfma_f32_16x16x32_bf16 v[82:85], v[86:89], v[204:207], v[82:85]
	s_setprio 0
	s_setprio 1
	v_mfma_f32_16x16x32_bf16 v[46:49], v[156:159], v[172:175], v[46:49]
	v_mfma_f32_16x16x32_bf16 v[14:17], v[164:167], v[172:175], v[14:17]
	v_mfma_f32_16x16x32_bf16 v[42:45], v[156:159], v[180:183], v[42:45]
	v_mfma_f32_16x16x32_bf16 v[10:13], v[164:167], v[180:183], v[10:13]
	v_mfma_f32_16x16x32_bf16 v[38:41], v[156:159], v[188:191], v[38:41]
	v_mfma_f32_16x16x32_bf16 v[6:9], v[164:167], v[188:191], v[6:9]
	v_mfma_f32_16x16x32_bf16 v[30:33], v[156:159], v[200:203], v[30:33]
	v_mfma_f32_16x16x32_bf16 v[2:5], v[164:167], v[200:203], v[2:5]
	v_mfma_f32_16x16x32_bf16 v[46:49], v[160:163], v[176:179], v[46:49]
	v_mfma_f32_16x16x32_bf16 v[14:17], v[168:171], v[176:179], v[14:17]
	v_mfma_f32_16x16x32_bf16 v[42:45], v[160:163], v[184:187], v[42:45]
	v_mfma_f32_16x16x32_bf16 v[10:13], v[168:171], v[184:187], v[10:13]
	v_mfma_f32_16x16x32_bf16 v[38:41], v[160:163], v[192:195], v[38:41]
	v_mfma_f32_16x16x32_bf16 v[6:9], v[168:171], v[192:195], v[6:9]
	v_mfma_f32_16x16x32_bf16 v[30:33], v[160:163], v[204:207], v[30:33]
	v_mfma_f32_16x16x32_bf16 v[2:5], v[168:171], v[204:207], v[2:5]
	s_setprio 0
	s_barrier
; #define PG8_STAGE(bufoff, gbase, voff) do { _Pragma("unroll") for (int _i = 0; _i < 2; ++_i) \
;         __builtin_amdgcn_global_load_lds((const unsigned*)((const char*)(gbase) + (voff)[_i]), (LAS unsigned*)(lds + (bufoff) + ldsw + _i * 8192), 16, 0, 0); } while (0)
; #define PG8_LDA(dst, b, h) do { _Pragma("unroll") for (int m = 0; m < 4; ++m) _Pragma("unroll") for (int k = 0; k < 2; ++k) dst[m][k] = *(const LAS bf16x8*)(lds + PG8_SA(b, h) + aoff + m * 2048 + k * 1024); } while (0)
; #define PG8_LDB(dst, b, h) do { _Pragma("unroll") for (int n = 0; n < 2; ++n) _Pragma("unroll") for (int k = 0; k < 2; ++k) dst[n][k] = *(const LAS bf16x8*)(lds + PG8_SB(b, h) + boff + n * 2048 + k * 1024); } while (0)
; #define PG8_MMA(ai, bj, At, Bt) do { __builtin_amdgcn_s_setprio(1); _Pragma("unroll") for (int m = 0; m < 4; ++m) _Pragma("unroll") for (int n = 0; n < 2; ++n) _Pragma("unroll") for (int k = 0; k < 2; ++k) \
;         acc[ai][bj][m][n] = __builtin_amdgcn_mfma_f32_16x16x32_bf16(Bt[n][k], At[m][k], acc[ai][bj][m][n], 0, 0, 0); __builtin_amdgcn_s_setprio(0); } while (0)
; #define PG8_WAIT_V(n) asm volatile("s_waitcnt vmcnt(" #n ")" ::: "memory")
; #define PG8_WAIT_L(n) asm volatile("s_waitcnt lgkmcnt(" #n ")" ::: "memory")
; #define PG8_BAR __builtin_amdgcn_s_barrier()
; #define PG8_SCHED __builtin_amdgcn_sched_barrier(0)
; template <class Epi, class Sched>
; __device__ __forceinline__ void gemm_phase(LAS unsigned char* lds, const int lda, const int ldb, const int K, const Sched& S, const Epi& E, int tid) {
;     ...
;             PG8_LDB(B0, 1, 0); PG8_LDB(B1, 1, 1); PG8_SCHED; PG8_LDA(At, 1, 0); PG8_STAGE(PG8_SA(0, 1), a2 + hA, voffA);
;             PG8_WAIT_V(8); PG8_WAIT_L(0); PG8_BAR; PG8_MMA(0, 0, At, B0); PG8_MMA(0, 1, At, B1); PG8_BAR; PG8_SCHED;
;             PG8_LDA(At, 1, 1); PG8_STAGE(PG8_SB(1, 0), b3, voffB); PG8_STAGE(PG8_SB(1, 1), b3 + hB, voffB); PG8_STAGE(PG8_SA(1, 0), a3, voffA);
;             PG8_WAIT_V(8); PG8_WAIT_L(0); PG8_BAR; PG8_MMA(1, 0, At, B0); PG8_MMA(1, 1, At, B1); PG8_BAR; PG8_SCHED;
;         }
;         if (wr == 0) PG8_BAR;
	s_add_i32 s33, 0, 0x18000
	s_add_i32 s34, 0, 0x1c000
	v_add_u32_e32 v130, s33, v208
	v_add_u32_e32 v168, s34, v208
	ds_read_b128 v[86:89], v130
	ds_read_b128 v[106:109], v130 offset:1024
	ds_read_b128 v[126:129], v130 offset:2048
	ds_read_b128 v[130:133], v130 offset:3072
	ds_read_b128 v[156:159], v168
	ds_read_b128 v[160:163], v168 offset:1024
	ds_read_b128 v[164:167], v168 offset:2048
	ds_read_b128 v[168:171], v168 offset:3072
	s_add_u32 s2, s8, 0x160000
	s_addc_u32 s3, s9, 0
	s_mov_b32 m0, s17
	ds_read_b128 v[172:175], v210 offset:32768
	ds_read_b128 v[176:179], v210 offset:33792
	ds_read_b128 v[180:183], v210 offset:34816
	ds_read_b128 v[184:187], v210 offset:35840
	ds_read_b128 v[188:191], v210 offset:36864
	ds_read_b128 v[192:195], v210 offset:37888
	ds_read_b128 v[200:203], v210 offset:38912
	ds_read_b128 v[204:207], v210 offset:39936
	global_load_lds_dwordx4 v146, s[2:3]
	s_mov_b32 m0, s18
	s_nop 0
	global_load_lds_dwordx4 v148, s[2:3]
	s_waitcnt vmcnt(8)
	s_waitcnt lgkmcnt(0)
	s_barrier
	s_setprio 1
	v_mfma_f32_16x16x32_bf16 v[142:145], v[86:89], v[172:175], v[142:145]
	v_mfma_f32_16x16x32_bf16 v[102:105], v[126:129], v[172:175], v[102:105]
	v_mfma_f32_16x16x32_bf16 v[138:141], v[86:89], v[180:183], v[138:141]
	v_mfma_f32_16x16x32_bf16 v[98:101], v[126:129], v[180:183], v[98:101]
	v_mfma_f32_16x16x32_bf16 v[134:137], v[86:89], v[188:191], v[134:137]
	v_mfma_f32_16x16x32_bf16 v[94:97], v[126:129], v[188:191], v[94:97]
	v_mfma_f32_16x16x32_bf16 v[122:125], v[86:89], v[200:203], v[122:125]
	v_mfma_f32_16x16x32_bf16 v[90:93], v[126:129], v[200:203], v[90:93]
	v_mfma_f32_16x16x32_bf16 v[142:145], v[106:109], v[176:179], v[142:145]
	v_mfma_f32_16x16x32_bf16 v[102:105], v[130:133], v[176:179], v[102:105]
	v_mfma_f32_16x16x32_bf16 v[138:141], v[106:109], v[184:187], v[138:141]
	v_mfma_f32_16x16x32_bf16 v[98:101], v[130:133], v[184:187], v[98:101]
	v_mfma_f32_16x16x32_bf16 v[134:137], v[106:109], v[192:195], v[134:137]
	v_mfma_f32_16x16x32_bf16 v[94:97], v[130:133], v[192:195], v[94:97]
	v_mfma_f32_16x16x32_bf16 v[122:125], v[106:109], v[204:207], v[122:125]
	v_mfma_f32_16x16x32_bf16 v[90:93], v[130:133], v[204:207], v[90:93]
	s_setprio 0
	s_setprio 1
	v_mfma_f32_16x16x32_bf16 v[66:69], v[156:159], v[172:175], v[66:69]
	v_mfma_f32_16x16x32_bf16 v[34:37], v[164:167], v[172:175], v[34:37]
	v_mfma_f32_16x16x32_bf16 v[58:61], v[156:159], v[180:183], v[58:61]
	v_mfma_f32_16x16x32_bf16 v[26:29], v[164:167], v[180:183], v[26:29]
	v_mfma_f32_16x16x32_bf16 v[54:57], v[156:159], v[188:191], v[54:57]
	v_mfma_f32_16x16x32_bf16 v[22:25], v[164:167], v[188:191], v[22:25]
	v_mfma_f32_16x16x32_bf16 v[50:53], v[156:159], v[200:203], v[50:53]
	v_mfma_f32_16x16x32_bf16 v[18:21], v[164:167], v[200:203], v[18:21]
	v_mfma_f32_16x16x32_bf16 v[66:69], v[160:163], v[176:179], v[66:69]
	v_mfma_f32_16x16x32_bf16 v[34:37], v[168:171], v[176:179], v[34:37]
	v_mfma_f32_16x16x32_bf16 v[58:61], v[160:163], v[184:187], v[58:61]
	v_mfma_f32_16x16x32_bf16 v[26:29], v[168:171], v[184:187], v[26:29]
	v_mfma_f32_16x16x32_bf16 v[54:57], v[160:163], v[192:195], v[54:57]
	v_mfma_f32_16x16x32_bf16 v[22:25], v[168:171], v[192:195], v[22:25]
	v_mfma_f32_16x16x32_bf16 v[50:53], v[160:163], v[204:207], v[50:53]
	v_mfma_f32_16x16x32_bf16 v[18:21], v[168:171], v[204:207], v[18:21]
	s_setprio 0
	s_barrier
	s_add_i32 s2, s33, s14
	s_mov_b32 m0, s2
	ds_read_b128 v[172:175], v210 offset:49152
	ds_read_b128 v[176:179], v210 offset:50176
	ds_read_b128 v[180:183], v210 offset:51200
	ds_read_b128 v[184:187], v210 offset:52224
	ds_read_b128 v[188:191], v210 offset:53248
	ds_read_b128 v[192:195], v210 offset:54272
	ds_read_b128 v[200:203], v210 offset:55296
	ds_read_b128 v[204:207], v210 offset:56320
	global_load_lds_dwordx4 v0, s[98:99]
	s_add_i32 m0, s2, 0x2000
	s_add_u32 s2, s6, 0x160080
	s_addc_u32 s3, s7, 0
	s_add_i32 s6, s34, s14
	global_load_lds_dwordx4 v150, s[98:99]
	s_mov_b32 m0, s6
	s_nop 0
	global_load_lds_dwordx4 v0, s[2:3]
	s_add_i32 m0, s6, 0x2000
	s_nop 0
	global_load_lds_dwordx4 v150, s[2:3]
	s_mov_b32 m0, s19
	s_nop 0
	global_load_lds_dwordx4 v146, s[100:101]
	s_mov_b32 m0, s20
	s_nop 0
	global_load_lds_dwordx4 v148, s[100:101]
	s_waitcnt vmcnt(8)
	s_waitcnt lgkmcnt(0)
	s_barrier
	s_setprio 1
	s_add_i32 s29, s29, 2
	s_add_u32 s25, s25, 0x100
	s_addc_u32 s28, s28, 0
	s_cmpk_gt_u32 s29, 0x55
	s_mov_b64 s[2:3], s[4:5]
	v_mfma_f32_16x16x32_bf16 v[118:121], v[86:89], v[172:175], v[118:121]
	v_mfma_f32_16x16x32_bf16 v[78:81], v[126:129], v[172:175], v[78:81]
	v_mfma_f32_16x16x32_bf16 v[114:117], v[86:89], v[180:183], v[114:117]
	v_mfma_f32_16x16x32_bf16 v[74:77], v[126:129], v[180:183], v[74:77]
	v_mfma_f32_16x16x32_bf16 v[110:113], v[86:89], v[188:191], v[110:113]
	v_mfma_f32_16x16x32_bf16 v[70:73], v[126:129], v[188:191], v[70:73]
	v_mfma_f32_16x16x32_bf16 v[82:85], v[86:89], v[200:203], v[82:85]
	v_mfma_f32_16x16x32_bf16 v[62:65], v[126:129], v[200:203], v[62:65]
	v_mfma_f32_16x16x32_bf16 v[118:121], v[106:109], v[176:179], v[118:121]
	v_mfma_f32_16x16x32_bf16 v[78:81], v[130:133], v[176:179], v[78:81]
	v_mfma_f32_16x16x32_bf16 v[114:117], v[106:109], v[184:187], v[114:117]
	v_mfma_f32_16x16x32_bf16 v[74:77], v[130:133], v[184:187], v[74:77]
	v_mfma_f32_16x16x32_bf16 v[110:113], v[106:109], v[192:195], v[110:113]
	v_mfma_f32_16x16x32_bf16 v[70:73], v[130:133], v[192:195], v[70:73]
	v_mfma_f32_16x16x32_bf16 v[106:109], v[106:109], v[204:207], v[82:85]
	v_mfma_f32_16x16x32_bf16 v[62:65], v[130:133], v[204:207], v[62:65]
	s_setprio 0
	s_setprio 1
	v_mfma_f32_16x16x32_bf16 v[46:49], v[156:159], v[172:175], v[46:49]
	v_mfma_f32_16x16x32_bf16 v[14:17], v[164:167], v[172:175], v[14:17]
	v_mfma_f32_16x16x32_bf16 v[42:45], v[156:159], v[180:183], v[42:45]
	v_mfma_f32_16x16x32_bf16 v[10:13], v[164:167], v[180:183], v[10:13]
	v_mfma_f32_16x16x32_bf16 v[38:41], v[156:159], v[188:191], v[38:41]
	v_mfma_f32_16x16x32_bf16 v[6:9], v[164:167], v[188:191], v[6:9]
	v_mfma_f32_16x16x32_bf16 v[30:33], v[156:159], v[200:203], v[30:33]
	v_mfma_f32_16x16x32_bf16 v[2:5], v[164:167], v[200:203], v[2:5]
	v_mfma_f32_16x16x32_bf16 v[46:49], v[160:163], v[176:179], v[46:49]
	v_mfma_f32_16x16x32_bf16 v[14:17], v[168:171], v[176:179], v[14:17]
	v_mfma_f32_16x16x32_bf16 v[42:45], v[160:163], v[184:187], v[42:45]
	v_mfma_f32_16x16x32_bf16 v[10:13], v[168:171], v[184:187], v[10:13]
	v_mfma_f32_16x16x32_bf16 v[38:41], v[160:163], v[192:195], v[38:41]
	v_mfma_f32_16x16x32_bf16 v[6:9], v[168:171], v[192:195], v[6:9]
	v_mfma_f32_16x16x32_bf16 v[30:33], v[160:163], v[204:207], v[30:33]
	v_mfma_f32_16x16x32_bf16 v[2:5], v[168:171], v[204:207], v[2:5]
	s_setprio 0
	s_barrier
	s_cbranch_scc0 .LBB0_880
	s_and_b64 vcc, exec, s[46:47]
	s_cbranch_vccz .LBB0_883
	s_barrier
